# strategy: one static priority raise for the younger wave half in the three attention pair loops; per-cluster setprio flips replaced by nops; stagger sleep removed
# speedup vs baseline: 1.0118x; 1.0074x over previous
; #define ATT_ISSUE2(p_, st_) do { LAS unsigned char* sp_ = lds + (st_) * STG2; const int ta_ = dual ? (p_) : 2 * (p_), tb_ = dual ? (p_) : 2 * (p_) + 1; ATT_ISSUE1(u, ta_, sp_); ATT_ISSUEM(ta_, sp_ + 2 * STAGEB); \
;         if (dual || tb_ < u.ntiles) { ATT_ISSUE1(ub, tb_, sp_ + STAGEB); ATT_ISSUEM(tb_, sp_ + 2 * STAGEB + MSKB); } } while (0)
;     ...
;             asm volatile("s_waitcnt vmcnt(0)" ::: "memory");
;             __builtin_amdgcn_s_barrier(); asm volatile("" ::: "memory");
;             if (p + 1 < npairs) ATT_ISSUE2(p + 1, (p + 1) & 1);
.LBB0_579:
	s_add_i32 s27, s2, 1
	s_waitcnt vmcnt(0)
	s_barrier
	v_readlane_b32 s98, v254, 11
	s_nop 3
	s_cmp_lt_u32 s98, 4
	s_cbranch_scc1 .Lstag_579
	s_setprio 1

; #define LAS __attribute__((address_space(3)))
;     ...
;     auto QK = [&](const LAS unsigned char* sbase, f32x16& s0, f32x16& s1) {
;         const LAS unsigned char* kb = sbase + r32 * KSTR; const int kc0 = (koff >> 3) + hi;
; #pragma unroll
;         for (int r = 0; r < 16; ++r) { s0[r] = 0.f; s1[r] = 0.f; }
; #pragma unroll
;         for (int kh = 0; kh < NKS; kh += 4) {
;             bf16x8 ka[4][2];
; #pragma unroll
;             for (int ks = 0; ks < 4; ++ks) { const int ko = ((kc0 + 2 * (kh + ks)) ^ ksw) << 4; ka[ks][0] = *(const LAS bf16x8*)(kb + ko); ka[ks][1] = *(const LAS bf16x8*)(kb + 32 * KSTR + ko); }
;             __builtin_amdgcn_s_setprio(1);
; #pragma unroll
;             for (int ks = 0; ks < 4; ++ks) { s0 = __builtin_amdgcn_mfma_f32_32x32x16_bf16(ka[ks][0], qf[kh + ks], s0, 0, 0, 0); s1 = __builtin_amdgcn_mfma_f32_32x32x16_bf16(ka[ks][1], qf[kh + ks], s1, 0, 0, 0); }
;             __builtin_amdgcn_s_setprio(0);
;         }
;     };
;     ...
;             if (wka) QK(sa, a0, a1);
;             if (LAYER == 0) { if (wkb) QK(sbb, b0, b1); }
.LBB0_582:
	s_bitcmp1_b32 s2, 0
	s_cselect_b32 s1, 0x10400, 0
	s_add_i32 s1, s1, 0
	s_cmp_le_u32 s74, s9
	v_add_u32_e32 v148, s1, v195
	s_cselect_b64 s[28:29], -1, 0
	s_cmp_gt_u32 s74, s9
	v_add_u32_e32 v151, v148, v196
	v_add_u32_e32 v150, v148, v197
	v_add_u32_e32 v149, v148, v198
	v_add_u32_e32 v148, v148, v199
	s_cbranch_scc1 .LBB0_584
	ds_read_b128 v[68:71], v151
	ds_read_b128 v[100:103], v151 offset:8192
	ds_read_b128 v[152:155], v150
	ds_read_b128 v[156:159], v150 offset:8192
	ds_read_b128 v[160:163], v149
	ds_read_b128 v[200:203], v149 offset:8192
	ds_read_b128 v[204:207], v148
	ds_read_b128 v[208:211], v148 offset:8192
	s_nop 0
	s_waitcnt lgkmcnt(0)
	v_mfma_f32_32x32x16_bf16 v[68:83], v[68:71], v[132:135], 0
	v_mfma_f32_32x32x16_bf16 v[100:115], v[100:103], v[132:135], 0
	v_mfma_f32_32x32x16_bf16 v[68:83], v[152:155], v[136:139], v[68:83]
	v_mfma_f32_32x32x16_bf16 v[100:115], v[156:159], v[136:139], v[100:115]
	v_mfma_f32_32x32x16_bf16 v[68:83], v[160:163], v[140:143], v[68:83]
	v_mfma_f32_32x32x16_bf16 v[100:115], v[200:203], v[140:143], v[100:115]
	v_mfma_f32_32x32x16_bf16 v[68:83], v[204:207], v[144:147], v[68:83]
	v_mfma_f32_32x32x16_bf16 v[100:115], v[208:211], v[144:147], v[100:115]
	s_nop 0
.LBB0_584:
	s_add_i32 s2, s74, 1
	s_cmp_lt_u32 s2, s75
	s_cselect_b64 s[2:3], -1, 0
	s_cmp_lt_u32 s74, s9
	s_cselect_b64 s[30:31], -1, 0
	s_and_b64 s[30:31], s[2:3], s[30:31]
	v_cndmask_b32_e64 v152, 0, 1, s[30:31]
	v_cmp_ne_u32_e64 s[2:3], 1, v152
	s_andn2_b64 vcc, exec, s[30:31]
	s_cbranch_vccnz .LBB0_586
	ds_read_b128 v[84:87], v151 offset:32768
	ds_read_b128 v[116:119], v151 offset:40960
	ds_read_b128 v[152:155], v150 offset:32768
	ds_read_b128 v[156:159], v150 offset:40960
	ds_read_b128 v[160:163], v149 offset:32768
	ds_read_b128 v[200:203], v149 offset:40960
	ds_read_b128 v[204:207], v148 offset:32768
	ds_read_b128 v[148:151], v148 offset:40960
	s_nop 0
	s_waitcnt lgkmcnt(0)
	v_mfma_f32_32x32x16_bf16 v[84:99], v[84:87], v[132:135], 0
	v_mfma_f32_32x32x16_bf16 v[116:131], v[116:119], v[132:135], 0
	v_mfma_f32_32x32x16_bf16 v[84:99], v[152:155], v[136:139], v[84:99]
	v_mfma_f32_32x32x16_bf16 v[116:131], v[156:159], v[136:139], v[116:131]
	v_mfma_f32_32x32x16_bf16 v[84:99], v[160:163], v[140:143], v[84:99]
	v_mfma_f32_32x32x16_bf16 v[116:131], v[200:203], v[140:143], v[116:131]
	v_mfma_f32_32x32x16_bf16 v[84:99], v[204:207], v[144:147], v[84:99]
	v_mfma_f32_32x32x16_bf16 v[116:131], v[148:151], v[144:147], v[116:131]
	s_nop 0

; __device__ __forceinline__ unsigned cvtpk(float lo, float hi) { typedef __bf16 b2 __attribute__((ext_vector_type(2))); f32x2 v = {lo, hi}; b2 b = __builtin_convertvector(v, b2); return __builtin_bit_cast(unsigned, b); }
; __device__ __forceinline__ int crow(int r, int hi) { return (r & 3) + 8 * (r >> 2) + 4 * hi; }
;     ...
;         const bool need = mx > mrun + 8.f;
;         if (__any(need)) { const float mnew = need ? mx : mrun, alpha = __builtin_amdgcn_exp2f(mrun - mnew); mrun = mnew; lrun *= alpha;
; #pragma unroll
;             for (int d = 0; d < 4; ++d)
; #pragma unroll
;                 for (int r = 0; r < 16; ++r) o[d][r] *= alpha; }
;         float rsa[4] = {0.f, 0.f, 0.f, 0.f};
; #pragma unroll
;         for (int r = 0; r < 16; ++r) { float p0 = __builtin_amdgcn_exp2f(s0[r] - mrun), p1 = __builtin_amdgcn_exp2f(s1[r] - mrun);
;             if (LAYER == 1) { const int kv = crow(r, hi); p0 = ((w0 >> kv) & 1u) ? p0 : 0.f; p1 = ((w1 >> kv) & 1u) ? p1 : 0.f; }
;             s0[r] = p0; s1[r] = p1; rsa[r & 3] += p0 + p1; }
;         lrun += (rsa[0] + rsa[1]) + (rsa[2] + rsa[3]);
; #pragma unroll
;         for (int s = 0; s < 2; ++s) {
;             v4u x; x.x = cvtpk(s0[8 * s + 0], s0[8 * s + 1]); x.y = cvtpk(s0[8 * s + 2], s0[8 * s + 3]); x.z = cvtpk(s0[8 * s + 4], s0[8 * s + 5]); x.w = cvtpk(s0[8 * s + 6], s0[8 * s + 7]); pb[0][s] = __builtin_bit_cast(bf16x8, x);
;             v4u y; y.x = cvtpk(s1[8 * s + 0], s1[8 * s + 1]); y.y = cvtpk(s1[8 * s + 2], s1[8 * s + 3]); y.z = cvtpk(s1[8 * s + 4], s1[8 * s + 5]); y.w = cvtpk(s1[8 * s + 6], s1[8 * s + 7]); pb[1][s] = __builtin_bit_cast(bf16x8, y); }
;     ...
;             if (wka) { vb = sa + KBUF + vlane; ATT_VREAD(vpre, 0); SM(wa0, wa1, a0, a1, pba);
;                 ATT_VREAD(va, 1); __builtin_amdgcn_s_setprio(1); ATT_PV(vpre, pba, 0); __builtin_amdgcn_s_setprio(0);
;                 ATT_VREAD(vbb, 2); __builtin_amdgcn_s_setprio(1); ATT_PV(va, pba, 1); __builtin_amdgcn_s_setprio(0);
;                 ATT_VREAD(va, 3); __builtin_amdgcn_s_setprio(1); ATT_PV(vbb, pba, 2); __builtin_amdgcn_s_setprio(0);
;                 __builtin_amdgcn_s_setprio(1); ATT_PV(va, pba, 3); __builtin_amdgcn_s_setprio(0); }
.LBB0_589:
	v_sub_f32_e32 v68, v68, v170
	v_sub_f32_e32 v100, v100, v170
	v_sub_f32_e32 v70, v70, v170
	v_sub_f32_e32 v102, v102, v170
	v_exp_f32_e32 v68, v68
	v_exp_f32_e32 v100, v100
	v_sub_f32_e32 v69, v69, v170
	v_sub_f32_e32 v101, v101, v170
	v_exp_f32_e32 v70, v70
	v_exp_f32_e32 v102, v102
	v_sub_f32_e32 v71, v71, v170
	v_sub_f32_e32 v103, v103, v170
	v_exp_f32_e32 v69, v69
	v_exp_f32_e32 v101, v101
	v_exp_f32_e32 v71, v71
	v_exp_f32_e32 v103, v103
	v_sub_f32_e32 v72, v72, v170
	v_sub_f32_e32 v104, v104, v170
	v_sub_f32_e32 v74, v74, v170
	v_sub_f32_e32 v106, v106, v170
	v_exp_f32_e32 v72, v72
	v_exp_f32_e32 v104, v104
	v_exp_f32_e32 v74, v74
	v_exp_f32_e32 v106, v106
	v_sub_f32_e32 v73, v73, v170
	v_sub_f32_e32 v105, v105, v170
	v_sub_f32_e32 v75, v75, v170
	v_sub_f32_e32 v107, v107, v170
	v_exp_f32_e32 v73, v73
	v_exp_f32_e32 v105, v105
	v_exp_f32_e32 v75, v75
	v_exp_f32_e32 v107, v107
	v_sub_f32_e32 v76, v76, v170
	v_sub_f32_e32 v108, v108, v170
	v_sub_f32_e32 v78, v78, v170
	v_sub_f32_e32 v110, v110, v170
	v_exp_f32_e32 v76, v76
	v_exp_f32_e32 v108, v108
	v_exp_f32_e32 v78, v78
	v_exp_f32_e32 v110, v110
	v_sub_f32_e32 v77, v77, v170
	v_sub_f32_e32 v109, v109, v170
	v_sub_f32_e32 v79, v79, v170
	v_sub_f32_e32 v111, v111, v170
	v_exp_f32_e32 v77, v77
	v_exp_f32_e32 v109, v109
	v_exp_f32_e32 v79, v79
	v_exp_f32_e32 v111, v111
	v_sub_f32_e32 v80, v80, v170
	v_sub_f32_e32 v112, v112, v170
	v_sub_f32_e32 v82, v82, v170
	v_sub_f32_e32 v114, v114, v170
	ds_read_b64_tr_b16 v[220:221], v200 offset:20480
	ds_read_b64_tr_b16 v[222:223], v201 offset:22528
	ds_read_b64_tr_b16 v[224:225], v202 offset:20480
	ds_read_b64_tr_b16 v[226:227], v203 offset:22528
	ds_read_b64_tr_b16 v[228:229], v204 offset:20480
	ds_read_b64_tr_b16 v[230:231], v205 offset:22528
	ds_read_b64_tr_b16 v[232:233], v206 offset:20480
	ds_read_b64_tr_b16 v[234:235], v207 offset:22528
	v_exp_f32_e32 v80, v80
	v_exp_f32_e32 v112, v112
	v_exp_f32_e32 v82, v82
	v_exp_f32_e32 v114, v114
	v_sub_f32_e32 v81, v81, v170
	v_sub_f32_e32 v113, v113, v170
	v_sub_f32_e32 v83, v83, v170
	v_sub_f32_e32 v115, v115, v170
	v_exp_f32_e32 v81, v81
	v_exp_f32_e32 v113, v113
	v_exp_f32_e32 v83, v83
	v_exp_f32_e32 v115, v115
	s_nop 0
	v_pk_add_f32 v[208:209], v[68:69], v[70:71]
	v_pk_add_f32 v[210:211], v[72:73], v[74:75]
	v_pk_add_f32 v[212:213], v[76:77], v[78:79]
	v_pk_add_f32 v[214:215], v[80:81], v[82:83]
	v_pk_add_f32 v[208:209], v[208:209], v[100:101]
	v_pk_add_f32 v[210:211], v[210:211], v[102:103]
	v_pk_add_f32 v[212:213], v[212:213], v[104:105]
	v_pk_add_f32 v[214:215], v[214:215], v[106:107]
	v_pk_add_f32 v[208:209], v[208:209], v[108:109]
	v_pk_add_f32 v[210:211], v[210:211], v[110:111]
	v_pk_add_f32 v[212:213], v[212:213], v[112:113]
	v_pk_add_f32 v[214:215], v[214:215], v[114:115]
	v_pk_add_f32 v[208:209], v[208:209], v[210:211]
	v_pk_add_f32 v[212:213], v[212:213], v[214:215]
	v_pk_add_f32 v[208:209], v[208:209], v[212:213]
	v_add_f32_e32 v240, v208, v209
	v_cvt_pk_bf16_f32 v214, v104, v105
	v_cvt_pk_bf16_f32 v212, v100, v101
	v_cvt_pk_bf16_f32 v210, v72, v73
	v_cvt_pk_bf16_f32 v208, v68, v69
	v_cvt_pk_bf16_f32 v209, v70, v71
	v_cvt_pk_bf16_f32 v211, v74, v75
	v_cvt_pk_bf16_f32 v213, v102, v103
	v_cvt_pk_bf16_f32 v215, v106, v107
	v_cvt_pk_bf16_f32 v216, v76, v77
	v_cvt_pk_bf16_f32 v217, v78, v79
	v_cvt_pk_bf16_f32 v218, v80, v81
	v_cvt_pk_bf16_f32 v219, v82, v83
	v_cvt_pk_bf16_f32 v236, v108, v109
	v_cvt_pk_bf16_f32 v237, v110, v111
	v_cvt_pk_bf16_f32 v238, v112, v113
	v_cvt_pk_bf16_f32 v239, v114, v115
	s_nop 0
	s_waitcnt lgkmcnt(8)
	v_mfma_f32_32x32x16_bf16 v[52:67], v[152:155], v[208:211], v[52:67]
	v_add_f32_e32 v167, v167, v240
	v_mfma_f32_32x32x16_bf16 v[36:51], v[148:151], v[208:211], v[36:51]
	v_mfma_f32_32x32x16_bf16 v[20:35], v[160:163], v[208:211], v[20:35]
	v_mfma_f32_32x32x16_bf16 v[4:19], v[156:159], v[208:211], v[4:19]
	s_nop 0
	ds_read_b64_tr_b16 v[148:149], v200 offset:24576
	ds_read_b64_tr_b16 v[150:151], v201 offset:26624
	ds_read_b64_tr_b16 v[152:153], v202 offset:24576
	ds_read_b64_tr_b16 v[154:155], v203 offset:26624
	ds_read_b64_tr_b16 v[156:157], v204 offset:24576
	ds_read_b64_tr_b16 v[158:159], v205 offset:26624
	ds_read_b64_tr_b16 v[160:161], v206 offset:24576
	ds_read_b64_tr_b16 v[162:163], v207 offset:26624
	s_nop 0
	s_waitcnt lgkmcnt(14)
	v_mfma_f32_32x32x16_bf16 v[52:67], v[220:223], v[216:219], v[52:67]
	s_waitcnt lgkmcnt(12)
	v_mfma_f32_32x32x16_bf16 v[36:51], v[224:227], v[216:219], v[36:51]
	s_waitcnt lgkmcnt(10)
	v_mfma_f32_32x32x16_bf16 v[20:35], v[228:231], v[216:219], v[20:35]
	s_waitcnt lgkmcnt(8)
	v_mfma_f32_32x32x16_bf16 v[4:19], v[232:235], v[216:219], v[4:19]
	s_nop 0
	ds_read_b64_tr_b16 v[208:209], v200 offset:28672
	ds_read_b64_tr_b16 v[210:211], v201 offset:30720
	ds_read_b64_tr_b16 v[216:217], v202 offset:28672
	ds_read_b64_tr_b16 v[218:219], v203 offset:30720
	ds_read_b64_tr_b16 v[220:221], v204 offset:28672
	ds_read_b64_tr_b16 v[222:223], v205 offset:30720
	ds_read_b64_tr_b16 v[224:225], v206 offset:28672
	ds_read_b64_tr_b16 v[226:227], v207 offset:30720
	s_nop 0
	s_waitcnt lgkmcnt(14)
	v_mfma_f32_32x32x16_bf16 v[52:67], v[148:151], v[212:215], v[52:67]
	s_waitcnt lgkmcnt(12)
	v_mfma_f32_32x32x16_bf16 v[36:51], v[152:155], v[212:215], v[36:51]
	s_waitcnt lgkmcnt(10)
	v_mfma_f32_32x32x16_bf16 v[20:35], v[156:159], v[212:215], v[20:35]
	s_waitcnt lgkmcnt(8)
	v_mfma_f32_32x32x16_bf16 v[4:19], v[160:163], v[212:215], v[4:19]
	s_nop 0
	s_nop 0
	s_waitcnt lgkmcnt(6)
	v_mfma_f32_32x32x16_bf16 v[52:67], v[208:211], v[236:239], v[52:67]
	s_waitcnt lgkmcnt(4)
	v_mfma_f32_32x32x16_bf16 v[36:51], v[216:219], v[236:239], v[36:51]
	s_waitcnt lgkmcnt(2)
	v_mfma_f32_32x32x16_bf16 v[20:35], v[220:223], v[236:239], v[20:35]
	s_waitcnt lgkmcnt(0)
	v_mfma_f32_32x32x16_bf16 v[4:19], v[224:227], v[236:239], v[4:19]
	s_nop 0

; __device__ __forceinline__ unsigned cvtpk(float lo, float hi) { typedef __bf16 b2 __attribute__((ext_vector_type(2))); f32x2 v = {lo, hi}; b2 b = __builtin_convertvector(v, b2); return __builtin_bit_cast(unsigned, b); }
; __device__ __forceinline__ int crow(int r, int hi) { return (r & 3) + 8 * (r >> 2) + 4 * hi; }
;     ...
;         if (__any(need)) { const float mnew = need ? mx : mrun, alpha = __builtin_amdgcn_exp2f(mrun - mnew); mrun = mnew; lrun *= alpha;
; #pragma unroll
;             for (int d = 0; d < 4; ++d)
; #pragma unroll
;                 for (int r = 0; r < 16; ++r) o[d][r] *= alpha; }
;         float rsa[4] = {0.f, 0.f, 0.f, 0.f};
; #pragma unroll
;         for (int r = 0; r < 16; ++r) { float p0 = __builtin_amdgcn_exp2f(s0[r] - mrun), p1 = __builtin_amdgcn_exp2f(s1[r] - mrun);
;             if (LAYER == 1) { const int kv = crow(r, hi); p0 = ((w0 >> kv) & 1u) ? p0 : 0.f; p1 = ((w1 >> kv) & 1u) ? p1 : 0.f; }
;             s0[r] = p0; s1[r] = p1; rsa[r & 3] += p0 + p1; }
;         lrun += (rsa[0] + rsa[1]) + (rsa[2] + rsa[3]);
; #pragma unroll
;         for (int s = 0; s < 2; ++s) {
;             v4u x; x.x = cvtpk(s0[8 * s + 0], s0[8 * s + 1]); x.y = cvtpk(s0[8 * s + 2], s0[8 * s + 3]); x.z = cvtpk(s0[8 * s + 4], s0[8 * s + 5]); x.w = cvtpk(s0[8 * s + 6], s0[8 * s + 7]); pb[0][s] = __builtin_bit_cast(bf16x8, x);
;             v4u y; y.x = cvtpk(s1[8 * s + 0], s1[8 * s + 1]); y.y = cvtpk(s1[8 * s + 2], s1[8 * s + 3]); y.z = cvtpk(s1[8 * s + 4], s1[8 * s + 5]); y.w = cvtpk(s1[8 * s + 6], s1[8 * s + 7]); pb[1][s] = __builtin_bit_cast(bf16x8, y); }
;     ...
;             if (wkb) { vb = sbb + KBUF + vlane; ATT_VREAD(vpre, 0); SM(wb0, wb1, b0, b1, pbb);
;                 ATT_VREAD(va, 1); __builtin_amdgcn_s_setprio(1); ATT_PV(vpre, pbb, 0); __builtin_amdgcn_s_setprio(0);
;                 ATT_VREAD(vbb, 2); __builtin_amdgcn_s_setprio(1); ATT_PV(va, pbb, 1); __builtin_amdgcn_s_setprio(0);
;                 ATT_VREAD(va, 3); __builtin_amdgcn_s_setprio(1); ATT_PV(vbb, pbb, 2); __builtin_amdgcn_s_setprio(0);
;                 __builtin_amdgcn_s_setprio(1); ATT_PV(va, pbb, 3); __builtin_amdgcn_s_setprio(0); }
.LBB0_593:
	v_sub_f32_e32 v84, v84, v170
	v_sub_f32_e32 v116, v116, v170
	v_sub_f32_e32 v86, v86, v170
	v_sub_f32_e32 v118, v118, v170
	v_exp_f32_e32 v84, v84
	v_exp_f32_e32 v116, v116
	v_sub_f32_e32 v85, v85, v170
	v_sub_f32_e32 v117, v117, v170
	v_exp_f32_e32 v86, v86
	v_exp_f32_e32 v118, v118
	v_sub_f32_e32 v87, v87, v170
	v_sub_f32_e32 v119, v119, v170
	v_exp_f32_e32 v85, v85
	v_exp_f32_e32 v117, v117
	v_exp_f32_e32 v87, v87
	v_exp_f32_e32 v119, v119
	v_sub_f32_e32 v88, v88, v170
	v_sub_f32_e32 v120, v120, v170
	v_sub_f32_e32 v90, v90, v170
	v_sub_f32_e32 v122, v122, v170
	v_exp_f32_e32 v88, v88
	v_exp_f32_e32 v120, v120
	v_exp_f32_e32 v90, v90
	v_exp_f32_e32 v122, v122
	v_sub_f32_e32 v89, v89, v170
	v_sub_f32_e32 v121, v121, v170
	v_sub_f32_e32 v91, v91, v170
	v_sub_f32_e32 v123, v123, v170
	v_exp_f32_e32 v89, v89
	v_exp_f32_e32 v121, v121
	v_exp_f32_e32 v91, v91
	v_exp_f32_e32 v123, v123
	v_sub_f32_e32 v92, v92, v170
	v_sub_f32_e32 v124, v124, v170
	v_sub_f32_e32 v94, v94, v170
	v_sub_f32_e32 v126, v126, v170
	v_exp_f32_e32 v92, v92
	v_exp_f32_e32 v124, v124
	v_exp_f32_e32 v94, v94
	v_exp_f32_e32 v126, v126
	v_sub_f32_e32 v93, v93, v170
	v_sub_f32_e32 v125, v125, v170
	v_sub_f32_e32 v95, v95, v170
	v_sub_f32_e32 v127, v127, v170
	v_exp_f32_e32 v93, v93
	v_exp_f32_e32 v125, v125
	v_exp_f32_e32 v95, v95
	v_exp_f32_e32 v127, v127
	v_sub_f32_e32 v96, v96, v170
	v_sub_f32_e32 v128, v128, v170
	v_sub_f32_e32 v98, v98, v170
	v_sub_f32_e32 v130, v130, v170
	ds_read_b64_tr_b16 v[220:221], v200 offset:53248
	ds_read_b64_tr_b16 v[222:223], v201 offset:55296
	ds_read_b64_tr_b16 v[224:225], v202 offset:53248
	ds_read_b64_tr_b16 v[226:227], v203 offset:55296
	ds_read_b64_tr_b16 v[228:229], v204 offset:53248
	ds_read_b64_tr_b16 v[230:231], v205 offset:55296
	ds_read_b64_tr_b16 v[232:233], v206 offset:53248
	ds_read_b64_tr_b16 v[234:235], v207 offset:55296
	v_exp_f32_e32 v96, v96
	v_exp_f32_e32 v128, v128
	v_exp_f32_e32 v98, v98
	v_exp_f32_e32 v130, v130
	v_sub_f32_e32 v97, v97, v170
	v_sub_f32_e32 v129, v129, v170
	v_sub_f32_e32 v99, v99, v170
	v_sub_f32_e32 v131, v131, v170
	v_exp_f32_e32 v97, v97
	v_exp_f32_e32 v129, v129
	v_exp_f32_e32 v99, v99
	v_exp_f32_e32 v131, v131
	s_nop 0
	v_pk_add_f32 v[208:209], v[84:85], v[86:87]
	v_pk_add_f32 v[210:211], v[88:89], v[90:91]
	v_pk_add_f32 v[212:213], v[92:93], v[94:95]
	v_pk_add_f32 v[214:215], v[96:97], v[98:99]
	v_pk_add_f32 v[208:209], v[208:209], v[116:117]
	v_pk_add_f32 v[210:211], v[210:211], v[118:119]
	v_pk_add_f32 v[212:213], v[212:213], v[120:121]
	v_pk_add_f32 v[214:215], v[214:215], v[122:123]
	v_pk_add_f32 v[208:209], v[208:209], v[124:125]
	v_pk_add_f32 v[210:211], v[210:211], v[126:127]
	v_pk_add_f32 v[212:213], v[212:213], v[128:129]
	v_pk_add_f32 v[214:215], v[214:215], v[130:131]
	v_pk_add_f32 v[208:209], v[208:209], v[210:211]
	v_pk_add_f32 v[212:213], v[212:213], v[214:215]
	v_pk_add_f32 v[208:209], v[208:209], v[212:213]
	v_add_f32_e32 v240, v208, v209
	v_cvt_pk_bf16_f32 v214, v120, v121
	v_cvt_pk_bf16_f32 v212, v116, v117
	v_cvt_pk_bf16_f32 v210, v88, v89
	v_cvt_pk_bf16_f32 v208, v84, v85
	v_cvt_pk_bf16_f32 v209, v86, v87
	v_cvt_pk_bf16_f32 v211, v90, v91
	v_cvt_pk_bf16_f32 v213, v118, v119
	v_cvt_pk_bf16_f32 v215, v122, v123
	v_cvt_pk_bf16_f32 v216, v92, v93
	v_cvt_pk_bf16_f32 v217, v94, v95
	v_cvt_pk_bf16_f32 v218, v96, v97
	v_cvt_pk_bf16_f32 v219, v98, v99
	v_cvt_pk_bf16_f32 v236, v124, v125
	v_cvt_pk_bf16_f32 v237, v126, v127
	v_cvt_pk_bf16_f32 v238, v128, v129
	v_cvt_pk_bf16_f32 v239, v130, v131
	s_nop 0
	s_waitcnt lgkmcnt(8)
	v_mfma_f32_32x32x16_bf16 v[52:67], v[152:155], v[208:211], v[52:67]
	v_add_f32_e32 v167, v167, v240
	v_mfma_f32_32x32x16_bf16 v[36:51], v[148:151], v[208:211], v[36:51]
	v_mfma_f32_32x32x16_bf16 v[20:35], v[160:163], v[208:211], v[20:35]
	v_mfma_f32_32x32x16_bf16 v[4:19], v[156:159], v[208:211], v[4:19]
	s_nop 0
	ds_read_b64_tr_b16 v[148:149], v200 offset:57344
	ds_read_b64_tr_b16 v[150:151], v201 offset:59392
	ds_read_b64_tr_b16 v[152:153], v202 offset:57344
	ds_read_b64_tr_b16 v[154:155], v203 offset:59392
	ds_read_b64_tr_b16 v[156:157], v204 offset:57344
	ds_read_b64_tr_b16 v[158:159], v205 offset:59392
	ds_read_b64_tr_b16 v[160:161], v206 offset:57344
	ds_read_b64_tr_b16 v[162:163], v207 offset:59392
	s_nop 0
	s_waitcnt lgkmcnt(14)
	v_mfma_f32_32x32x16_bf16 v[52:67], v[220:223], v[216:219], v[52:67]
	s_waitcnt lgkmcnt(12)
	v_mfma_f32_32x32x16_bf16 v[36:51], v[224:227], v[216:219], v[36:51]
	s_waitcnt lgkmcnt(10)
	v_mfma_f32_32x32x16_bf16 v[20:35], v[228:231], v[216:219], v[20:35]
	s_waitcnt lgkmcnt(8)
	v_mfma_f32_32x32x16_bf16 v[4:19], v[232:235], v[216:219], v[4:19]
	s_nop 0
	ds_read_b64_tr_b16 v[208:209], v200 offset:61440
	ds_read_b64_tr_b16 v[210:211], v201 offset:63488
	ds_read_b64_tr_b16 v[200:201], v202 offset:61440
	ds_read_b64_tr_b16 v[202:203], v203 offset:63488
	ds_read_b64_tr_b16 v[216:217], v204 offset:61440
	ds_read_b64_tr_b16 v[218:219], v205 offset:63488
	ds_read_b64_tr_b16 v[204:205], v206 offset:61440
	ds_read_b64_tr_b16 v[206:207], v207 offset:63488
	s_nop 0
	s_waitcnt lgkmcnt(14)
	v_mfma_f32_32x32x16_bf16 v[52:67], v[148:151], v[212:215], v[52:67]
	s_waitcnt lgkmcnt(12)
	v_mfma_f32_32x32x16_bf16 v[36:51], v[152:155], v[212:215], v[36:51]
	s_waitcnt lgkmcnt(10)
	v_mfma_f32_32x32x16_bf16 v[20:35], v[156:159], v[212:215], v[20:35]
	s_waitcnt lgkmcnt(8)
	v_mfma_f32_32x32x16_bf16 v[4:19], v[160:163], v[212:215], v[4:19]
	s_nop 0
	s_nop 0
	s_waitcnt lgkmcnt(6)
	v_mfma_f32_32x32x16_bf16 v[52:67], v[208:211], v[236:239], v[52:67]
	s_waitcnt lgkmcnt(4)
	v_mfma_f32_32x32x16_bf16 v[36:51], v[200:203], v[236:239], v[36:51]
	s_waitcnt lgkmcnt(2)
	v_mfma_f32_32x32x16_bf16 v[20:35], v[216:219], v[236:239], v[20:35]
	s_waitcnt lgkmcnt(0)
	v_mfma_f32_32x32x16_bf16 v[4:19], v[204:207], v[236:239], v[4:19]
	s_nop 0

; #define LAS __attribute__((address_space(3)))
;     ...
;         asm volatile("s_waitcnt lgkmcnt(0)" ::: "memory"); __builtin_amdgcn_s_barrier(); asm volatile("" ::: "memory");
;     ...
;     const float ltot = lrun + __shfl_xor(lrun, 32);
;     const float inv = active ? __builtin_amdgcn_rcpf(ltot) : 0.f;
;     if (u.split >= 0) {
;         if (active) { const int hd = LAYER == 0 ? myhead * 2 + map : u.head * 4 + r4;
;             float* pr = (float*)(F.ws + WS_APART) + (((size_t)u.split * NS + (qrow - NP)) * 32 + hd) * 130;
; #pragma unroll
;             for (int d = 0; d < 4; ++d)
; #pragma unroll
;                 for (int rg = 0; rg < 4; ++rg) { float* p = pr + d * 32 + 8 * rg + 4 * hi; p[0] = o[d][4 * rg]; p[1] = o[d][4 * rg + 1]; p[2] = o[d][4 * rg + 2]; p[3] = o[d][4 * rg + 3]; }
;             if (hi == 0) { pr[128] = mrun; pr[129] = ltot; } }
;         return;
;     }
;     bf16* OB = (bf16*)(F.ws + WS_OB);
;     if (LAYER == 0) {
;         LAS float* xch = (LAS float*)lds;
;         if (map == 1 && active) { const float sc = inv * lam;
; #pragma unroll
;             for (int d = 0; d < 4; ++d)
; #pragma unroll
;                 for (int r = 0; r < 16; ++r) xch[(sb * 64 + d * 16 + r) * 64 + lane] = o[d][r] * sc; }
.LBB0_597:
	s_setprio 0
	v_and_b32_e32 v68, 64, v184
	v_xor_b32_e32 v2, 32, v184
	v_add_u32_e32 v68, 64, v68
	v_cmp_lt_i32_e32 vcc, v2, v68
	s_waitcnt lgkmcnt(0)
	s_barrier
	s_lshl_b32 s2, s85, 7
	v_cndmask_b32_e32 v2, v184, v2, vcc
	v_lshlrev_b32_e32 v161, 2, v2
	ds_bpermute_b32 v2, v161, v167
	v_and_b32_e32 v160, 63, v171
	s_cmp_lt_i32 s26, 0
	s_mov_b64 s[0:1], -1
	s_waitcnt lgkmcnt(0)
	v_add_f32_e32 v171, v167, v2
	s_cbranch_scc0 .LBB0_603
	v_rcp_f32_e32 v78, v171
	s_andn2_b64 vcc, exec, s[14:15]
	s_cbranch_vccnz .LBB0_600
	v_mul_f32_e32 v2, v1, v78
	v_readlane_b32 s0, v254, 37
	v_mul_f32_e32 v68, v52, v2
	v_mul_f32_e32 v70, v53, v2
	v_lshl_add_u32 v69, v160, 2, s0
	ds_write2st64_b32 v69, v68, v70 offset1:1
	v_mul_f32_e32 v68, v54, v2
	v_mul_f32_e32 v70, v55, v2
	ds_write2st64_b32 v69, v68, v70 offset0:2 offset1:3
	v_mul_f32_e32 v68, v56, v2
	v_mul_f32_e32 v70, v57, v2
	ds_write2st64_b32 v69, v68, v70 offset0:4 offset1:5
	v_mul_f32_e32 v68, v58, v2
	v_mul_f32_e32 v70, v59, v2
	ds_write2st64_b32 v69, v68, v70 offset0:6 offset1:7
	v_mul_f32_e32 v68, v60, v2
	v_mul_f32_e32 v70, v61, v2
	ds_write2st64_b32 v69, v68, v70 offset0:8 offset1:9
	v_mul_f32_e32 v68, v62, v2
	v_mul_f32_e32 v70, v63, v2
	ds_write2st64_b32 v69, v68, v70 offset0:10 offset1:11
	v_mul_f32_e32 v68, v64, v2
	v_mul_f32_e32 v70, v65, v2
	ds_write2st64_b32 v69, v68, v70 offset0:12 offset1:13
	v_mul_f32_e32 v68, v66, v2
	v_mul_f32_e32 v70, v67, v2
	ds_write2st64_b32 v69, v68, v70 offset0:14 offset1:15
	v_mul_f32_e32 v68, v36, v2
	v_mul_f32_e32 v70, v37, v2
	ds_write2st64_b32 v69, v68, v70 offset0:16 offset1:17
	v_mul_f32_e32 v68, v38, v2
	v_mul_f32_e32 v70, v39, v2
	ds_write2st64_b32 v69, v68, v70 offset0:18 offset1:19
	v_mul_f32_e32 v68, v40, v2
	v_mul_f32_e32 v70, v41, v2
	ds_write2st64_b32 v69, v68, v70 offset0:20 offset1:21
	v_mul_f32_e32 v68, v42, v2
	v_mul_f32_e32 v70, v43, v2
	ds_write2st64_b32 v69, v68, v70 offset0:22 offset1:23
	v_mul_f32_e32 v68, v44, v2
	v_mul_f32_e32 v70, v45, v2
	ds_write2st64_b32 v69, v68, v70 offset0:24 offset1:25
	v_mul_f32_e32 v68, v46, v2
	v_mul_f32_e32 v70, v47, v2
	ds_write2st64_b32 v69, v68, v70 offset0:26 offset1:27
	v_mul_f32_e32 v68, v48, v2
	v_mul_f32_e32 v70, v49, v2
	ds_write2st64_b32 v69, v68, v70 offset0:28 offset1:29
	v_mul_f32_e32 v68, v50, v2
	v_mul_f32_e32 v70, v51, v2
	ds_write2st64_b32 v69, v68, v70 offset0:30 offset1:31
	v_mul_f32_e32 v68, v20, v2
	v_mul_f32_e32 v70, v21, v2
	ds_write2st64_b32 v69, v68, v70 offset0:32 offset1:33
	v_mul_f32_e32 v68, v22, v2
	v_mul_f32_e32 v70, v23, v2
	ds_write2st64_b32 v69, v68, v70 offset0:34 offset1:35
	v_mul_f32_e32 v68, v24, v2
	v_mul_f32_e32 v70, v25, v2
	ds_write2st64_b32 v69, v68, v70 offset0:36 offset1:37
	v_mul_f32_e32 v68, v26, v2
	v_mul_f32_e32 v70, v27, v2
	ds_write2st64_b32 v69, v68, v70 offset0:38 offset1:39
	v_mul_f32_e32 v68, v28, v2
	v_mul_f32_e32 v70, v29, v2
	ds_write2st64_b32 v69, v68, v70 offset0:40 offset1:41
	v_mul_f32_e32 v68, v30, v2
	v_mul_f32_e32 v70, v31, v2
	ds_write2st64_b32 v69, v68, v70 offset0:42 offset1:43
	v_mul_f32_e32 v68, v32, v2
	v_mul_f32_e32 v70, v33, v2
	ds_write2st64_b32 v69, v68, v70 offset0:44 offset1:45
	v_mul_f32_e32 v68, v34, v2
	v_mul_f32_e32 v70, v35, v2
	ds_write2st64_b32 v69, v68, v70 offset0:46 offset1:47
	v_mul_f32_e32 v68, v4, v2
	v_mul_f32_e32 v70, v5, v2
	ds_write2st64_b32 v69, v68, v70 offset0:48 offset1:49
	v_mul_f32_e32 v68, v6, v2
	v_mul_f32_e32 v70, v7, v2
	ds_write2st64_b32 v69, v68, v70 offset0:50 offset1:51
	v_mul_f32_e32 v68, v8, v2
	v_mul_f32_e32 v70, v9, v2
	ds_write2st64_b32 v69, v68, v70 offset0:52 offset1:53
	v_mul_f32_e32 v68, v10, v2
	v_mul_f32_e32 v70, v11, v2
	ds_write2st64_b32 v69, v68, v70 offset0:54 offset1:55
	v_mul_f32_e32 v68, v12, v2
	v_mul_f32_e32 v70, v13, v2
	ds_write2st64_b32 v69, v68, v70 offset0:56 offset1:57
	v_mul_f32_e32 v68, v14, v2
	v_mul_f32_e32 v70, v15, v2
	ds_write2st64_b32 v69, v68, v70 offset0:58 offset1:59
	v_mul_f32_e32 v68, v16, v2
	v_mul_f32_e32 v70, v17, v2
	ds_write2st64_b32 v69, v68, v70 offset0:60 offset1:61
	v_mul_f32_e32 v68, v18, v2
	v_mul_f32_e32 v2, v19, v2
	ds_write2st64_b32 v69, v68, v2 offset0:62 offset1:63

; __device__ __forceinline__ void p_attn_b(Frame& F) {
;     ...
;     for (int slot = slot0; slot < 256; slot += F.G) {
;         for (int part = 0; part < 2; ++part) { const bool do_sample = ((slot >> 3) & 1) ? (part == 1) : (part == 0);
;             if (do_sample) { const int bg = slot >> 3, sp = slot & 7;
;                 AttnUnit u; u.cv = 0; u.dual = 0; u.head2 = 0; u.samp = 1; u.b = bg >> 2; u.head = bg & 3; u.qb = 0; u.qrow0 = NP + u.b * TS; u.t0 = 8 * sp; u.ntiles = sp == 7 ? 65 : 8 * sp + 8; u.split = sp; attn_unit<1, false>(F, u, 0, 0.f, 0.f); }
;             else { const int x = slot & 7, i = slot >> 3;
;                 for (int r = 0; r < 2; ++r) { const int bg = 2 * x + r;
;                     AttnUnit u; u.cv = 0; u.dual = 0; u.head2 = 0; u.samp = 0; u.b = bg >> 2; u.head = bg & 3; u.qb = r ? 31 - i : i; u.qrow0 = u.b * TP + u.qb * 64; u.ntiles = u.qb + 1; u.t0 = 0; u.split = -1; attn_unit<1, true>(F, u, 0, 0.f, 0.f); } }
.LBB0_2093:
	s_setprio 0
	v_mov_b32_e32 v82, v160
	s_movk_i32 s12, 0x210

; #define ATT_ISSUE2(p_, st_) do { LAS unsigned char* sp_ = lds + (st_) * STG2; const int ta_ = dual ? (p_) : 2 * (p_), tb_ = dual ? (p_) : 2 * (p_) + 1; ATT_ISSUE1(u, ta_, sp_); ATT_ISSUEM(ta_, sp_ + 2 * STAGEB); \
;         if (dual || tb_ < u.ntiles) { ATT_ISSUE1(ub, tb_, sp_ + STAGEB); ATT_ISSUEM(tb_, sp_ + 2 * STAGEB + MSKB); } } while (0)
;     ...
;             asm volatile("s_waitcnt vmcnt(0)" ::: "memory");
;             __builtin_amdgcn_s_barrier(); asm volatile("" ::: "memory");
;             if (p + 1 < npairs) ATT_ISSUE2(p + 1, (p + 1) & 1);
.LBB0_2104:
	s_waitcnt vmcnt(0)
	s_barrier
	v_readlane_b32 s98, v254, 11
	s_nop 3
	s_cmp_lt_u32 s98, 4
	s_cbranch_scc1 .Lstag_2104
	s_setprio 1

; #define LAS __attribute__((address_space(3)))
; __device__ __forceinline__ int crow(int r, int hi) { return (r & 3) + 8 * (r >> 2) + 4 * hi; }
;     ...
;     auto QK = [&](const LAS unsigned char* sbase, f32x16& s0, f32x16& s1) {
;         const LAS unsigned char* kb = sbase + r32 * KSTR; const int kc0 = (koff >> 3) + hi;
; #pragma unroll
;         for (int r = 0; r < 16; ++r) { s0[r] = 0.f; s1[r] = 0.f; }
; #pragma unroll
;         for (int kh = 0; kh < NKS; kh += 4) {
;             bf16x8 ka[4][2];
; #pragma unroll
;             for (int ks = 0; ks < 4; ++ks) { const int ko = ((kc0 + 2 * (kh + ks)) ^ ksw) << 4; ka[ks][0] = *(const LAS bf16x8*)(kb + ko); ka[ks][1] = *(const LAS bf16x8*)(kb + 32 * KSTR + ko); }
;             __builtin_amdgcn_s_setprio(1);
; #pragma unroll
;             for (int ks = 0; ks < 4; ++ks) { s0 = __builtin_amdgcn_mfma_f32_32x32x16_bf16(ka[ks][0], qf[kh + ks], s0, 0, 0, 0); s1 = __builtin_amdgcn_mfma_f32_32x32x16_bf16(ka[ks][1], qf[kh + ks], s1, 0, 0, 0); }
;             __builtin_amdgcn_s_setprio(0);
;         }
;     };
;     auto SM = [&](unsigned w0, unsigned w1, f32x16& s0, f32x16& s1, bf16x8 (&pb)[2][2]) {
;         if (LAYER == 1) {
; #pragma unroll
;             for (int r = 0; r < 16; ++r) { const int kv = crow(r, hi); if (!((w0 >> kv) & 1u)) s0[r] = -1e30f; if (!((w1 >> kv) & 1u)) s1[r] = -1e30f; } }
;         float mx = fmaxf(s0[0], s1[0]);
; #pragma unroll
;         for (int r = 1; r < 16; ++r) mx = fmaxf(mx, fmaxf(s0[r], s1[r]));
;         mx = fmaxf(mx, __shfl_xor(mx, 32));
;     ...
;             if (LAYER == 1) { const v2u ma = *(const LAS v2u*)(sa + 2 * STAGEB + (32 * sb + r32) * 8), mb = *(const LAS v2u*)(sa + 2 * STAGEB + MSKB + (32 * sb + r32) * 8); wa0 = ma.x; wa1 = ma.y; wb0 = mb.x; wb1 = mb.y; }
;             if (wka) QK(sa, a0, a1);
;             if (LAYER == 0) { if (wkb) QK(sbb, b0, b1); }
.LBB0_2110:
	s_bitcmp1_b32 s4, 0
	s_cselect_b32 s0, 0x10400, 0
	s_add_i32 s0, s0, 0
	v_add_u32_e32 v82, s0, v172
	v_add_u32_e32 v83, 0x10200, v82
	s_waitcnt lgkmcnt(0)
	ds_read_b64 v[156:157], v83
	v_add_u32_e32 v83, s0, v173
	v_add_u32_e32 v84, s0, v171
	s_cmp_gt_i32 s85, s90
	v_add_u32_e32 v214, v83, v174
	v_add_u32_e32 v213, v83, v175
	v_add_u32_e32 v212, v83, v176
	v_add_u32_e32 v211, v83, v177
	v_add_u32_e32 v210, v83, v178
	v_add_u32_e32 v209, v83, v179
	v_add_u32_e32 v208, v83, v180
	v_add_u32_e32 v207, v83, v181
	v_add_u32_e32 v155, v84, v161
	v_add_u32_e32 v199, v84, v162
	v_add_u32_e32 v200, v84, v163
	v_add_u32_e32 v201, v84, v166
	v_add_u32_e32 v202, v84, v167
	v_add_u32_e32 v203, v84, v168
	v_add_u32_e32 v204, v84, v169
	v_add_u32_e32 v205, v84, v170
	s_cbranch_scc1 .LBB0_2114
	v_add_u32_e32 v82, 0x10000, v82
	ds_read_b64 v[240:241], v82
	ds_read_b128 v[82:85], v214
	ds_read_b128 v[98:101], v214 offset:8192
	ds_read_b128 v[102:105], v213
	ds_read_b128 v[134:137], v213 offset:8192
	ds_read_b128 v[106:109], v212
	ds_read_b128 v[138:141], v212 offset:8192
	ds_read_b128 v[110:113], v211
	ds_read_b128 v[216:219], v211 offset:8192
	s_nop 0
	s_waitcnt lgkmcnt(0)
	v_mfma_f32_32x32x16_bf16 v[82:97], v[82:85], v[4:7], 0
	v_mfma_f32_32x32x16_bf16 v[82:97], v[102:105], v[8:11], v[82:97]
	v_mfma_f32_32x32x16_bf16 v[82:97], v[106:109], v[12:15], v[82:97]
	v_mfma_f32_32x32x16_bf16 v[82:97], v[110:113], v[114:117], v[82:97]
	s_nop 0
	ds_read_b128 v[102:105], v210
	ds_read_b128 v[224:227], v210 offset:8192
	ds_read_b128 v[106:109], v209
	ds_read_b128 v[228:231], v209 offset:8192
	ds_read_b128 v[110:113], v208
	ds_read_b128 v[232:235], v208 offset:8192
	ds_read_b128 v[220:223], v207
	ds_read_b128 v[236:239], v207 offset:8192
	s_nop 0
	s_waitcnt lgkmcnt(0)
	v_mfma_f32_32x32x16_bf16 v[82:97], v[102:105], v[118:121], v[82:97]
	v_mfma_f32_32x32x16_bf16 v[82:97], v[106:109], v[122:125], v[82:97]
	v_mfma_f32_32x32x16_bf16 v[82:97], v[110:113], v[126:129], v[82:97]
	v_mfma_f32_32x32x16_bf16 v[82:97], v[220:223], v[130:133], v[82:97]
	s_nop 0
	v_mfma_f32_32x32x16_bf16 v[98:113], v[98:101], v[4:7], 0
	v_and_b32_e32 v215, v240, v182
	v_cmp_eq_u32_e64 s[20:21], 0, v215
	v_and_b32_e32 v221, v240, v183
	v_cmp_eq_u32_e64 s[10:11], 0, v221
	s_nop 5
	v_cndmask_b32_e64 v220, v82, v158, s[20:21]
	v_and_b32_e32 v82, v241, v183
	v_cmp_eq_u32_e64 s[66:67], 0, v82
	v_mfma_f32_32x32x16_bf16 v[98:113], v[134:137], v[8:11], v[98:113]
	v_and_b32_e32 v82, v240, v191
	v_cmp_eq_u32_e64 s[50:51], 0, v82
	v_and_b32_e32 v82, v241, v191
	v_cmp_eq_u32_e64 s[52:53], 0, v82
	v_and_b32_e32 v82, v240, v193
	v_cmp_eq_u32_e64 s[46:47], 0, v82
	v_and_b32_e32 v82, v241, v193
	v_mfma_f32_32x32x16_bf16 v[98:113], v[138:141], v[12:15], v[98:113]
	v_cmp_eq_u32_e64 s[48:49], 0, v82
	v_and_b32_e32 v82, v240, v194
	v_cmp_eq_u32_e64 s[40:41], 0, v82
	v_and_b32_e32 v82, v241, v194
	v_cmp_eq_u32_e64 s[42:43], 0, v82
	v_and_b32_e32 v82, v240, v195
	v_cmp_eq_u32_e64 s[36:37], 0, v82
	v_mfma_f32_32x32x16_bf16 v[98:113], v[216:219], v[114:117], v[98:113]
	v_and_b32_e32 v82, v241, v195
	v_cmp_eq_u32_e64 s[38:39], 0, v82
	v_and_b32_e32 v82, v240, v196
	v_cmp_eq_u32_e64 s[30:31], 0, v82
	v_and_b32_e32 v82, v241, v196
	v_cmp_eq_u32_e64 s[34:35], 0, v82
	v_and_b32_e32 v82, v240, v197
	v_mfma_f32_32x32x16_bf16 v[98:113], v[224:227], v[118:121], v[98:113]
	v_cndmask_b32_e64 v218, v83, v158, s[10:11]
	v_and_b32_e32 v83, v240, v184
	v_cmp_eq_u32_e64 s[26:27], 0, v82
	v_and_b32_e32 v82, v241, v197
	v_and_b32_e32 v242, v241, v184
	v_cmp_eq_u32_e64 s[18:19], 0, v83
	v_cmp_eq_u32_e64 s[28:29], 0, v82
	v_mfma_f32_32x32x16_bf16 v[98:113], v[228:231], v[122:125], v[98:113]
	v_and_b32_e32 v82, v240, v198
	v_and_b32_e32 v215, v240, v185
	v_cndmask_b32_e64 v222, v84, v158, s[18:19]
	v_and_b32_e32 v83, v241, v185
	v_and_b32_e32 v84, v240, v186
	v_cmp_eq_u32_e64 s[64:65], 0, v242
	v_cmp_eq_u32_e64 s[22:23], 0, v82
	v_mfma_f32_32x32x16_bf16 v[98:113], v[232:235], v[126:129], v[98:113]
	v_and_b32_e32 v82, v241, v198
	v_and_b32_e32 v223, v241, v182
	v_cmp_eq_u32_e64 s[8:9], 0, v215
	v_cmp_eq_u32_e64 s[16:17], 0, v84
	v_and_b32_e32 v84, v241, v187
	v_cmp_eq_u32_e64 s[62:63], 0, v83
	v_cmp_eq_u32_e64 s[24:25], 0, v82
	v_mfma_f32_32x32x16_bf16 v[98:113], v[236:239], v[130:133], v[98:113]
	s_nop 0
	v_cndmask_b32_e64 v217, v85, v158, s[8:9]
	v_and_b32_e32 v85, v241, v186
	v_cmp_eq_u32_e64 s[68:69], 0, v223
	v_cmp_eq_u32_e64 s[58:59], 0, v84
	s_nop 0
	v_and_b32_e32 v215, v240, v187
	s_nop 4
	v_cndmask_b32_e64 v230, v99, v158, s[66:67]
	v_cndmask_b32_e64 v229, v100, v158, s[64:65]
	v_cndmask_b32_e64 v228, v101, v158, s[62:63]
	v_cndmask_b32_e64 v231, v98, v158, s[68:69]
	v_cmp_eq_u32_e64 s[60:61], 0, v85
	v_cndmask_b32_e64 v221, v86, v158, s[16:17]
	v_cmp_eq_u32_e64 s[4:5], 0, v215
	v_cndmask_b32_e64 v227, v102, v158, s[60:61]
	v_cndmask_b32_e64 v215, v87, v158, s[4:5]
	v_and_b32_e32 v86, v240, v188
	v_and_b32_e32 v87, v241, v188
	v_cndmask_b32_e64 v226, v103, v158, s[58:59]
	v_and_b32_e32 v216, v240, v189
	v_cmp_eq_u32_e64 s[14:15], 0, v86
	v_and_b32_e32 v86, v241, v189
	v_cmp_eq_u32_e64 s[56:57], 0, v87
	v_cndmask_b32_e64 v219, v88, v158, s[14:15]
	v_cmp_eq_u32_e64 s[6:7], 0, v216
	v_cndmask_b32_e64 v225, v104, v158, s[56:57]
	v_cmp_eq_u32_e64 s[54:55], 0, v86
	v_cndmask_b32_e64 v216, v89, v158, s[6:7]
	v_and_b32_e32 v88, v240, v190
	v_and_b32_e32 v89, v241, v190
	v_cndmask_b32_e64 v223, v105, v158, s[54:55]
	v_cmp_eq_u32_e64 s[12:13], 0, v88
	v_cmp_eq_u32_e64 s[44:45], 0, v89
	v_cndmask_b32_e64 v90, v90, v158, s[12:13]
	v_cndmask_b32_e64 v224, v106, v158, s[44:45]
	v_cndmask_b32_e64 v105, v91, v158, s[50:51]
	v_cndmask_b32_e64 v106, v107, v158, s[52:53]
	v_cndmask_b32_e64 v103, v92, v158, s[46:47]
	v_cndmask_b32_e64 v104, v108, v158, s[48:49]
	v_cndmask_b32_e64 v101, v93, v158, s[40:41]
	v_cndmask_b32_e64 v102, v109, v158, s[42:43]
	v_cndmask_b32_e64 v99, v94, v158, s[36:37]
	v_cndmask_b32_e64 v100, v110, v158, s[38:39]
	v_cndmask_b32_e64 v95, v95, v158, s[30:31]
	v_cndmask_b32_e64 v98, v111, v158, s[34:35]
	v_cndmask_b32_e64 v93, v96, v158, s[26:27]
	v_cndmask_b32_e64 v94, v112, v158, s[28:29]
	v_cndmask_b32_e64 v91, v97, v158, s[22:23]
	v_cndmask_b32_e64 v92, v113, v158, s[24:25]
	v_max3_f32 v96, v220, v218, v222
	v_max3_f32 v247, v217, v230, v229
	v_max3_f32 v96, v96, v228, v231
	v_max3_f32 v247, v247, v221, v227
	v_max3_f32 v96, v96, v215, v226
	v_max3_f32 v247, v247, v219, v225
	v_max3_f32 v96, v96, v216, v223
	v_max3_f32 v247, v247, v90, v224
	v_max3_f32 v96, v96, v105, v106
	v_max3_f32 v247, v247, v103, v104
	v_max3_f32 v96, v96, v101, v102
	v_max3_f32 v247, v247, v99, v100
	v_max3_f32 v96, v96, v95, v98
	v_max3_f32 v247, v247, v93, v94
	v_max3_f32 v96, v96, v91, v92
	v_max_f32_e32 v96, v96, v247
	s_waitcnt vmcnt(0)
; __device__ __forceinline__ unsigned cvtpk(float lo, float hi) { typedef __bf16 b2 __attribute__((ext_vector_type(2))); f32x2 v = {lo, hi}; b2 b = __builtin_convertvector(v, b2); return __builtin_bit_cast(unsigned, b); }
; __device__ __forceinline__ int crow(int r, int hi) { return (r & 3) + 8 * (r >> 2) + 4 * hi; }
; #define ATT_VREAD(dst, q_) do { const LAS char* vp_ = (const LAS char*)vb + (((q_) >> 1) * 32 + 16 * ((q_) & 1)) * VSTR; \
;         _Pragma("unroll") for (int d_ = 0; d_ < 4; ++d_) { dst[d_][0] = vtr(vp_ + voff[d_][0]); dst[d_][1] = vtr(vp_ + 8 * VSTR + voff[d_][1]); } } while (0)
;     ...
;         mx = fmaxf(mx, __shfl_xor(mx, 32));
;         const bool need = mx > mrun + 8.f;
;         if (__any(need)) { const float mnew = need ? mx : mrun, alpha = __builtin_amdgcn_exp2f(mrun - mnew); mrun = mnew; lrun *= alpha;
; #pragma unroll
;             for (int d = 0; d < 4; ++d)
; #pragma unroll
;                 for (int r = 0; r < 16; ++r) o[d][r] *= alpha; }
;         float rsa[4] = {0.f, 0.f, 0.f, 0.f};
; #pragma unroll
;         for (int r = 0; r < 16; ++r) { float p0 = __builtin_amdgcn_exp2f(s0[r] - mrun), p1 = __builtin_amdgcn_exp2f(s1[r] - mrun);
;             if (LAYER == 1) { const int kv = crow(r, hi); p0 = ((w0 >> kv) & 1u) ? p0 : 0.f; p1 = ((w1 >> kv) & 1u) ? p1 : 0.f; }
;             s0[r] = p0; s1[r] = p1; rsa[r & 3] += p0 + p1; }
;         lrun += (rsa[0] + rsa[1]) + (rsa[2] + rsa[3]);
; #pragma unroll
;         for (int s = 0; s < 2; ++s) {
;             v4u x; x.x = cvtpk(s0[8 * s + 0], s0[8 * s + 1]); x.y = cvtpk(s0[8 * s + 2], s0[8 * s + 3]); x.z = cvtpk(s0[8 * s + 4], s0[8 * s + 5]); x.w = cvtpk(s0[8 * s + 6], s0[8 * s + 7]); pb[0][s] = __builtin_bit_cast(bf16x8, x);
;             v4u y; y.x = cvtpk(s1[8 * s + 0], s1[8 * s + 1]); y.y = cvtpk(s1[8 * s + 2], s1[8 * s + 3]); y.z = cvtpk(s1[8 * s + 4], s1[8 * s + 5]); y.w = cvtpk(s1[8 * s + 6], s1[8 * s + 7]); pb[1][s] = __builtin_bit_cast(bf16x8, y); }
;     };
;     ...
;             if (wka) { vb = sa + KBUF + vlane; ATT_VREAD(vpre, 0); SM(wa0, wa1, a0, a1, pba);
;                 ATT_VREAD(va, 1); __builtin_amdgcn_s_setprio(1); ATT_PV(vpre, pba, 0); __builtin_amdgcn_s_setprio(0);
	ds_read_b64_tr_b16 v[138:139], v155 offset:16384
	ds_read_b64_tr_b16 v[140:141], v199 offset:18432
	ds_read_b64_tr_b16 v[134:135], v200 offset:16384
	ds_read_b64_tr_b16 v[136:137], v201 offset:18432
	v_mov_b32_e32 v246, v96
	v_mov_b32_e32 v247, v96
	ds_read_b64_tr_b16 v[86:87], v202 offset:16384
	ds_read_b64_tr_b16 v[88:89], v203 offset:18432
	ds_read_b64_tr_b16 v[82:83], v204 offset:16384
	ds_read_b64_tr_b16 v[84:85], v205 offset:18432
	v_permlane32_swap_b32_e32 v246, v247
	v_max3_f32 v96, v96, v246, v247
	v_add_f32_e32 v97, 0x41000000, v206
	v_cmp_gt_f32_e32 vcc, v96, v97
	s_cbranch_vccz .LBB0_2113
	s_nop 0
	v_cndmask_b32_e32 v97, v206, v96, vcc
	v_sub_f32_e32 v96, v206, v97
	v_exp_f32_e32 v96, v96
	v_mov_b32_e32 v206, v97
	v_mul_f32_e32 v192, v192, v96
	v_pk_mul_f32 v[80:81], v[80:81], v[96:97] op_sel_hi:[1,0]
	v_pk_mul_f32 v[78:79], v[78:79], v[96:97] op_sel_hi:[1,0]
	v_pk_mul_f32 v[76:77], v[76:77], v[96:97] op_sel_hi:[1,0]
	v_pk_mul_f32 v[74:75], v[74:75], v[96:97] op_sel_hi:[1,0]
	v_pk_mul_f32 v[72:73], v[72:73], v[96:97] op_sel_hi:[1,0]
	v_pk_mul_f32 v[70:71], v[70:71], v[96:97] op_sel_hi:[1,0]
	v_pk_mul_f32 v[68:69], v[68:69], v[96:97] op_sel_hi:[1,0]
	v_pk_mul_f32 v[66:67], v[66:67], v[96:97] op_sel_hi:[1,0]
	v_pk_mul_f32 v[64:65], v[64:65], v[96:97] op_sel_hi:[1,0]
	v_pk_mul_f32 v[62:63], v[62:63], v[96:97] op_sel_hi:[1,0]
	v_pk_mul_f32 v[60:61], v[60:61], v[96:97] op_sel_hi:[1,0]
	v_pk_mul_f32 v[58:59], v[58:59], v[96:97] op_sel_hi:[1,0]
	v_pk_mul_f32 v[56:57], v[56:57], v[96:97] op_sel_hi:[1,0]
	v_pk_mul_f32 v[54:55], v[54:55], v[96:97] op_sel_hi:[1,0]
	v_pk_mul_f32 v[52:53], v[52:53], v[96:97] op_sel_hi:[1,0]
	v_pk_mul_f32 v[50:51], v[50:51], v[96:97] op_sel_hi:[1,0]
	v_pk_mul_f32 v[48:49], v[48:49], v[96:97] op_sel_hi:[1,0]
	v_pk_mul_f32 v[46:47], v[46:47], v[96:97] op_sel_hi:[1,0]
	v_pk_mul_f32 v[44:45], v[44:45], v[96:97] op_sel_hi:[1,0]
	v_pk_mul_f32 v[42:43], v[42:43], v[96:97] op_sel_hi:[1,0]
	v_pk_mul_f32 v[40:41], v[40:41], v[96:97] op_sel_hi:[1,0]
	v_pk_mul_f32 v[38:39], v[38:39], v[96:97] op_sel_hi:[1,0]
	v_pk_mul_f32 v[36:37], v[36:37], v[96:97] op_sel_hi:[1,0]
	v_pk_mul_f32 v[34:35], v[34:35], v[96:97] op_sel_hi:[1,0]
	v_pk_mul_f32 v[32:33], v[32:33], v[96:97] op_sel_hi:[1,0]
	v_pk_mul_f32 v[30:31], v[30:31], v[96:97] op_sel_hi:[1,0]
	v_pk_mul_f32 v[28:29], v[28:29], v[96:97] op_sel_hi:[1,0]
	v_pk_mul_f32 v[26:27], v[26:27], v[96:97] op_sel_hi:[1,0]
	v_pk_mul_f32 v[24:25], v[24:25], v[96:97] op_sel_hi:[1,0]
	v_pk_mul_f32 v[22:23], v[22:23], v[96:97] op_sel_hi:[1,0]
	v_pk_mul_f32 v[20:21], v[20:21], v[96:97] op_sel_hi:[1,0]
	v_pk_mul_f32 v[18:19], v[18:19], v[96:97] op_sel_hi:[1,0]
.LBB0_2113:
	v_max_f32_e32 v246, 0xef800000, v206
	v_sub_f32_e32 v96, v220, v246
	v_sub_f32_e32 v97, v231, v246
	v_exp_f32_e32 v96, v96
	v_exp_f32_e32 v97, v97
	v_sub_f32_e32 v107, v218, v246
	v_sub_f32_e32 v108, v230, v246
	v_sub_f32_e32 v220, v221, v246
	v_sub_f32_e32 v221, v227, v246
	v_exp_f32_e32 v107, v107
	v_exp_f32_e32 v108, v108
	v_sub_f32_e32 v110, v222, v246
	v_sub_f32_e32 v111, v229, v246
	v_exp_f32_e32 v220, v220
	v_exp_f32_e32 v221, v221
	v_sub_f32_e32 v215, v215, v246
	v_sub_f32_e32 v226, v226, v246
	v_exp_f32_e32 v110, v110
	v_exp_f32_e32 v111, v111
	v_sub_f32_e32 v113, v217, v246
	v_sub_f32_e32 v217, v228, v246
	v_exp_f32_e32 v215, v215
	v_exp_f32_e32 v226, v226
	v_sub_f32_e32 v219, v219, v246
	v_sub_f32_e32 v225, v225, v246
	v_exp_f32_e32 v113, v113
	v_exp_f32_e32 v217, v217
	v_exp_f32_e32 v219, v219
	v_exp_f32_e32 v225, v225
	v_sub_f32_e32 v216, v216, v246
	v_sub_f32_e32 v223, v223, v246
	v_exp_f32_e32 v216, v216
	v_exp_f32_e32 v223, v223
	v_add_f32_e32 v109, v96, v97
	v_sub_f32_e32 v90, v90, v246
	v_add_f32_e32 v109, 0, v109
	v_add_f32_e32 v112, v107, v108
	v_add_f32_e32 v227, v220, v221
	v_exp_f32_e32 v90, v90
	v_add_f32_e32 v112, 0, v112
	v_add_f32_e32 v218, v110, v111
	v_add_f32_e32 v109, v227, v109
	v_add_f32_e32 v227, v215, v226
	v_add_f32_e32 v218, 0, v218
	v_add_f32_e32 v222, v113, v217
	v_add_f32_e32 v112, v227, v112
	v_add_f32_e32 v227, v219, v225
	v_sub_f32_e32 v224, v224, v246
	v_add_f32_e32 v222, 0, v222
	v_add_f32_e32 v218, v227, v218
	v_exp_f32_e32 v224, v224
	v_add_f32_e32 v227, v216, v223
	v_add_f32_e32 v222, v227, v222
	v_mov_b32_e32 v227, v90
	v_sub_f32_e32 v90, v105, v246
	v_exp_f32_e32 v90, v90
	v_sub_f32_e32 v105, v106, v246
	v_add_f32_e32 v106, v227, v224
	v_add_f32_e32 v106, v106, v109
	v_mov_b32_e32 v109, v90
	v_sub_f32_e32 v90, v103, v246
	v_exp_f32_e32 v228, v105
	v_exp_f32_e32 v105, v90
	v_sub_f32_e32 v103, v104, v246
	v_exp_f32_e32 v229, v103
	v_sub_f32_e32 v90, v101, v246
	v_exp_f32_e32 v103, v90
	v_sub_f32_e32 v101, v102, v246
	v_exp_f32_e32 v230, v101
	v_sub_f32_e32 v90, v99, v246
	v_exp_f32_e32 v101, v90
	v_sub_f32_e32 v99, v100, v246
	v_exp_f32_e32 v99, v99
	v_sub_f32_e32 v90, v95, v246
	v_exp_f32_e32 v90, v90
	v_add_f32_e32 v100, v103, v230
	v_add_f32_e32 v100, v100, v222
	v_mov_b32_e32 v222, v99
	v_sub_f32_e32 v95, v98, v246
	v_exp_f32_e32 v231, v95
	v_add_f32_e32 v98, v101, v222
	v_add_f32_e32 v98, v98, v106
	v_mov_b32_e32 v106, v90
	v_sub_f32_e32 v90, v93, v246
	v_exp_f32_e32 v90, v90
	v_add_f32_e32 v104, v109, v228
	v_sub_f32_e32 v93, v94, v246
	v_add_f32_e32 v104, v104, v112
	v_exp_f32_e32 v232, v93
	v_add_f32_e32 v94, v106, v231
	v_add_f32_e32 v94, v94, v104
	v_mov_b32_e32 v104, v90
	v_sub_f32_e32 v90, v91, v246
	v_sub_f32_e32 v91, v92, v246
	v_exp_f32_e32 v90, v90
	v_exp_f32_e32 v233, v91
	v_add_f32_e32 v102, v105, v229
	v_add_f32_e32 v102, v102, v218
	v_add_f32_e32 v92, v104, v232
	v_add_f32_e32 v92, v92, v102
	v_mov_b32_e32 v102, v90
	v_add_f32_e32 v90, v102, v233
	v_add_f32_e32 v90, v90, v100
	v_add_f32_e32 v91, v98, v94
	v_add_f32_e32 v90, v92, v90
	v_add_f32_e32 v234, v91, v90
	v_cvt_pk_bf16_f32 v90, v96, v107
	v_cvt_pk_bf16_f32 v91, v110, v113
	v_cvt_pk_bf16_f32 v93, v219, v216
	v_cvt_pk_bf16_f32 v94, v97, v108
	v_cvt_pk_bf16_f32 v95, v111, v217
	v_cvt_pk_bf16_f32 v98, v227, v109
	v_cvt_pk_bf16_f32 v99, v105, v103
	v_cvt_pk_bf16_f32 v100, v101, v106
	v_cvt_pk_bf16_f32 v101, v104, v102
	ds_read_b64_tr_b16 v[102:103], v155 offset:20480
	ds_read_b64_tr_b16 v[104:105], v199 offset:22528
	ds_read_b64_tr_b16 v[106:107], v200 offset:20480
	ds_read_b64_tr_b16 v[108:109], v201 offset:22528
	ds_read_b64_tr_b16 v[110:111], v202 offset:20480
	ds_read_b64_tr_b16 v[112:113], v203 offset:22528
	ds_read_b64_tr_b16 v[216:217], v204 offset:20480
	ds_read_b64_tr_b16 v[218:219], v205 offset:22528
	v_cvt_pk_bf16_f32 v92, v220, v215
	v_cvt_pk_bf16_f32 v96, v221, v226
	v_cvt_pk_bf16_f32 v97, v225, v223
	v_cvt_pk_bf16_f32 v220, v224, v228
	v_cvt_pk_bf16_f32 v221, v229, v230
	v_cvt_pk_bf16_f32 v222, v222, v231
	v_cvt_pk_bf16_f32 v223, v232, v233
	s_nop 0
	s_waitcnt lgkmcnt(12)
; #define LAS __attribute__((address_space(3)))
; #define ATT_VREAD(dst, q_) do { const LAS char* vp_ = (const LAS char*)vb + (((q_) >> 1) * 32 + 16 * ((q_) & 1)) * VSTR; \
;         _Pragma("unroll") for (int d_ = 0; d_ < 4; ++d_) { dst[d_][0] = vtr(vp_ + voff[d_][0]); dst[d_][1] = vtr(vp_ + 8 * VSTR + voff[d_][1]); } } while (0)
; #define ATT_PV(src, pb_, q_) do { _Pragma("unroll") for (int d_ = 0; d_ < 4; ++d_) { const s16x4 lo_ = src[d_][0], hh_ = src[d_][1]; \
;         const bf16x8 vf_ = (bf16x8){lo_[0], lo_[1], lo_[2], lo_[3], hh_[0], hh_[1], hh_[2], hh_[3]}; o[d_] = __builtin_amdgcn_mfma_f32_32x32x16_bf16(vf_, pb_[(q_) >> 1][(q_) & 1], o[d_], 0, 0, 0); } } while (0)
;     ...
;     auto QK = [&](const LAS unsigned char* sbase, f32x16& s0, f32x16& s1) {
;         const LAS unsigned char* kb = sbase + r32 * KSTR; const int kc0 = (koff >> 3) + hi;
; #pragma unroll
;         for (int r = 0; r < 16; ++r) { s0[r] = 0.f; s1[r] = 0.f; }
; #pragma unroll
;         for (int kh = 0; kh < NKS; kh += 4) {
;             bf16x8 ka[4][2];
; #pragma unroll
;             for (int ks = 0; ks < 4; ++ks) { const int ko = ((kc0 + 2 * (kh + ks)) ^ ksw) << 4; ka[ks][0] = *(const LAS bf16x8*)(kb + ko); ka[ks][1] = *(const LAS bf16x8*)(kb + 32 * KSTR + ko); }
;             __builtin_amdgcn_s_setprio(1);
; #pragma unroll
;             for (int ks = 0; ks < 4; ++ks) { s0 = __builtin_amdgcn_mfma_f32_32x32x16_bf16(ka[ks][0], qf[kh + ks], s0, 0, 0, 0); s1 = __builtin_amdgcn_mfma_f32_32x32x16_bf16(ka[ks][1], qf[kh + ks], s1, 0, 0, 0); }
;             __builtin_amdgcn_s_setprio(0);
;         }
;     };
;     ...
;                 ATT_VREAD(va, 1); __builtin_amdgcn_s_setprio(1); ATT_PV(vpre, pba, 0); __builtin_amdgcn_s_setprio(0);
;                 ATT_VREAD(vbb, 2); __builtin_amdgcn_s_setprio(1); ATT_PV(va, pba, 1); __builtin_amdgcn_s_setprio(0);
;                 ATT_VREAD(va, 3); __builtin_amdgcn_s_setprio(1); ATT_PV(vbb, pba, 2); __builtin_amdgcn_s_setprio(0);
;                 __builtin_amdgcn_s_setprio(1); ATT_PV(va, pba, 3); __builtin_amdgcn_s_setprio(0); }
;             if (LAYER == 1) { if (wkb) QK(sbb, b0, b1); }
	v_mfma_f32_32x32x16_bf16 v[66:81], v[138:141], v[90:93], v[66:81]
	v_add_f32_e32 v192, v192, v234
	v_mfma_f32_32x32x16_bf16 v[50:65], v[134:137], v[90:93], v[50:65]
	s_waitcnt lgkmcnt(10)
	v_mfma_f32_32x32x16_bf16 v[34:49], v[86:89], v[90:93], v[34:49]
	s_waitcnt lgkmcnt(8)
	v_mfma_f32_32x32x16_bf16 v[18:33], v[82:85], v[90:93], v[18:33]
	s_nop 0
	ds_read_b64_tr_b16 v[82:83], v155 offset:24576
	ds_read_b64_tr_b16 v[84:85], v199 offset:26624
	ds_read_b64_tr_b16 v[86:87], v200 offset:24576
	ds_read_b64_tr_b16 v[88:89], v201 offset:26624
	ds_read_b64_tr_b16 v[90:91], v202 offset:24576
	ds_read_b64_tr_b16 v[92:93], v203 offset:26624
	ds_read_b64_tr_b16 v[134:135], v204 offset:24576
	ds_read_b64_tr_b16 v[136:137], v205 offset:26624
	s_nop 0
	s_waitcnt lgkmcnt(14)
	v_mfma_f32_32x32x16_bf16 v[66:81], v[102:105], v[98:101], v[66:81]
	s_waitcnt lgkmcnt(12)
	v_mfma_f32_32x32x16_bf16 v[50:65], v[106:109], v[98:101], v[50:65]
	s_waitcnt lgkmcnt(10)
	v_mfma_f32_32x32x16_bf16 v[34:49], v[110:113], v[98:101], v[34:49]
	s_waitcnt lgkmcnt(8)
	v_mfma_f32_32x32x16_bf16 v[18:33], v[216:219], v[98:101], v[18:33]
	s_nop 0
	ds_read_b64_tr_b16 v[98:99], v155 offset:28672
	ds_read_b64_tr_b16 v[100:101], v199 offset:30720
	ds_read_b64_tr_b16 v[102:103], v200 offset:28672
	ds_read_b64_tr_b16 v[104:105], v201 offset:30720
	ds_read_b64_tr_b16 v[106:107], v202 offset:28672
	ds_read_b64_tr_b16 v[108:109], v203 offset:30720
	ds_read_b64_tr_b16 v[110:111], v204 offset:28672
	ds_read_b64_tr_b16 v[112:113], v205 offset:30720
	s_nop 0
	s_waitcnt lgkmcnt(14)
	v_mfma_f32_32x32x16_bf16 v[66:81], v[82:85], v[94:97], v[66:81]
	s_waitcnt lgkmcnt(12)
	v_mfma_f32_32x32x16_bf16 v[50:65], v[86:89], v[94:97], v[50:65]
	s_waitcnt lgkmcnt(10)
	v_mfma_f32_32x32x16_bf16 v[34:49], v[90:93], v[94:97], v[34:49]
	s_waitcnt lgkmcnt(8)
	v_mfma_f32_32x32x16_bf16 v[18:33], v[134:137], v[94:97], v[18:33]
	s_nop 0
	s_nop 0
	s_waitcnt lgkmcnt(6)
	v_mfma_f32_32x32x16_bf16 v[66:81], v[98:101], v[220:223], v[66:81]
	s_waitcnt lgkmcnt(4)
	v_mfma_f32_32x32x16_bf16 v[50:65], v[102:105], v[220:223], v[50:65]
	s_waitcnt lgkmcnt(2)
	v_mfma_f32_32x32x16_bf16 v[34:49], v[106:109], v[220:223], v[34:49]
	s_waitcnt lgkmcnt(0)
	v_mfma_f32_32x32x16_bf16 v[18:33], v[110:113], v[220:223], v[18:33]
	s_nop 0
.LBB0_2114:
	s_cmp_ge_i32 s85, s90
	s_cbranch_scc1 .LBB0_2118
	ds_read_b128 v[82:85], v214 offset:32768
	ds_read_b128 v[98:101], v214 offset:40960
	ds_read_b128 v[102:105], v213 offset:32768
	ds_read_b128 v[134:137], v213 offset:40960
	ds_read_b128 v[106:109], v212 offset:32768
	ds_read_b128 v[138:141], v212 offset:40960
	ds_read_b128 v[110:113], v211 offset:32768
	ds_read_b128 v[214:217], v211 offset:40960
	s_nop 0
	s_waitcnt lgkmcnt(0)
	v_mfma_f32_32x32x16_bf16 v[82:97], v[82:85], v[4:7], 0
	v_mfma_f32_32x32x16_bf16 v[82:97], v[102:105], v[8:11], v[82:97]
	v_mfma_f32_32x32x16_bf16 v[82:97], v[106:109], v[12:15], v[82:97]
	v_mfma_f32_32x32x16_bf16 v[82:97], v[110:113], v[114:117], v[82:97]
	s_nop 0
	ds_read_b128 v[102:105], v210 offset:32768
	ds_read_b128 v[218:221], v210 offset:40960
	ds_read_b128 v[106:109], v209 offset:32768
	ds_read_b128 v[222:225], v209 offset:40960
	ds_read_b128 v[110:113], v208 offset:32768
	ds_read_b128 v[226:229], v208 offset:40960
	ds_read_b128 v[208:211], v207 offset:32768
	ds_read_b128 v[230:233], v207 offset:40960
	s_nop 0
	s_waitcnt lgkmcnt(0)
	v_mfma_f32_32x32x16_bf16 v[82:97], v[102:105], v[118:121], v[82:97]
	v_mfma_f32_32x32x16_bf16 v[82:97], v[106:109], v[122:125], v[82:97]
	v_mfma_f32_32x32x16_bf16 v[82:97], v[110:113], v[126:129], v[82:97]
	v_mfma_f32_32x32x16_bf16 v[82:97], v[208:211], v[130:133], v[82:97]
	s_nop 0
	v_mfma_f32_32x32x16_bf16 v[98:113], v[98:101], v[4:7], 0
	v_and_b32_e32 v207, v156, v182
	v_cmp_eq_u32_e64 s[20:21], 0, v207
	v_and_b32_e32 v208, v156, v183
	v_cmp_eq_u32_e64 s[10:11], 0, v208
	s_nop 5
	v_cndmask_b32_e64 v212, v82, v158, s[20:21]
	v_and_b32_e32 v82, v157, v183
	v_cmp_eq_u32_e64 s[66:67], 0, v82
	v_mfma_f32_32x32x16_bf16 v[98:113], v[134:137], v[8:11], v[98:113]
	v_and_b32_e32 v82, v156, v191
	v_cmp_eq_u32_e64 s[50:51], 0, v82
	v_and_b32_e32 v82, v157, v191
	v_cmp_eq_u32_e64 s[52:53], 0, v82
	v_and_b32_e32 v82, v156, v193
	v_cmp_eq_u32_e64 s[46:47], 0, v82
	v_and_b32_e32 v82, v157, v193
	v_mfma_f32_32x32x16_bf16 v[98:113], v[138:141], v[12:15], v[98:113]
	v_cmp_eq_u32_e64 s[48:49], 0, v82
	v_and_b32_e32 v82, v156, v194
	v_cmp_eq_u32_e64 s[40:41], 0, v82
	v_and_b32_e32 v82, v157, v194
	v_cmp_eq_u32_e64 s[42:43], 0, v82
	v_and_b32_e32 v82, v156, v195
	v_cmp_eq_u32_e64 s[36:37], 0, v82
	v_mfma_f32_32x32x16_bf16 v[98:113], v[214:217], v[114:117], v[98:113]
	v_and_b32_e32 v82, v157, v195
	v_cmp_eq_u32_e64 s[38:39], 0, v82
	v_and_b32_e32 v82, v156, v196
	v_cmp_eq_u32_e64 s[30:31], 0, v82
	v_and_b32_e32 v82, v157, v196
	v_cmp_eq_u32_e64 s[34:35], 0, v82
	v_and_b32_e32 v82, v156, v197
	v_mfma_f32_32x32x16_bf16 v[98:113], v[218:221], v[118:121], v[98:113]
	v_cndmask_b32_e64 v210, v83, v158, s[10:11]
	v_and_b32_e32 v83, v156, v184
	v_cmp_eq_u32_e64 s[26:27], 0, v82
	v_and_b32_e32 v82, v157, v197
	v_and_b32_e32 v215, v157, v184
	v_cmp_eq_u32_e64 s[18:19], 0, v83
	v_cmp_eq_u32_e64 s[28:29], 0, v82
	v_mfma_f32_32x32x16_bf16 v[98:113], v[222:225], v[122:125], v[98:113]
	v_and_b32_e32 v82, v156, v198
	v_and_b32_e32 v207, v156, v185
	v_cndmask_b32_e64 v214, v84, v158, s[18:19]
	v_and_b32_e32 v83, v157, v185
	v_and_b32_e32 v84, v156, v186
	v_cmp_eq_u32_e64 s[64:65], 0, v215
	v_cmp_eq_u32_e64 s[22:23], 0, v82
	v_mfma_f32_32x32x16_bf16 v[98:113], v[226:229], v[126:129], v[98:113]
	v_and_b32_e32 v82, v157, v198
	v_and_b32_e32 v234, v157, v182
	v_cmp_eq_u32_e64 s[8:9], 0, v207
; __device__ __forceinline__ int crow(int r, int hi) { return (r & 3) + 8 * (r >> 2) + 4 * hi; }
; #define ATT_VREAD(dst, q_) do { const LAS char* vp_ = (const LAS char*)vb + (((q_) >> 1) * 32 + 16 * ((q_) & 1)) * VSTR; \
;         _Pragma("unroll") for (int d_ = 0; d_ < 4; ++d_) { dst[d_][0] = vtr(vp_ + voff[d_][0]); dst[d_][1] = vtr(vp_ + 8 * VSTR + voff[d_][1]); } } while (0)
;     ...
;     auto SM = [&](unsigned w0, unsigned w1, f32x16& s0, f32x16& s1, bf16x8 (&pb)[2][2]) {
;         if (LAYER == 1) {
; #pragma unroll
;             for (int r = 0; r < 16; ++r) { const int kv = crow(r, hi); if (!((w0 >> kv) & 1u)) s0[r] = -1e30f; if (!((w1 >> kv) & 1u)) s1[r] = -1e30f; } }
;         float mx = fmaxf(s0[0], s1[0]);
; #pragma unroll
;         for (int r = 1; r < 16; ++r) mx = fmaxf(mx, fmaxf(s0[r], s1[r]));
;         mx = fmaxf(mx, __shfl_xor(mx, 32));
;         const bool need = mx > mrun + 8.f;
;         if (__any(need)) { const float mnew = need ? mx : mrun, alpha = __builtin_amdgcn_exp2f(mrun - mnew); mrun = mnew; lrun *= alpha;
; #pragma unroll
;             for (int d = 0; d < 4; ++d)
; #pragma unroll
;                 for (int r = 0; r < 16; ++r) o[d][r] *= alpha; }
;     ...
;             if (wkb) { vb = sbb + KBUF + vlane; ATT_VREAD(vpre, 0); SM(wb0, wb1, b0, b1, pbb);
	v_cmp_eq_u32_e64 s[16:17], 0, v84
	v_and_b32_e32 v84, v157, v187
	v_cmp_eq_u32_e64 s[62:63], 0, v83
	v_cmp_eq_u32_e64 s[24:25], 0, v82
	v_mfma_f32_32x32x16_bf16 v[98:113], v[230:233], v[130:133], v[98:113]
	s_nop 0
	v_cndmask_b32_e64 v209, v85, v158, s[8:9]
	v_and_b32_e32 v85, v157, v186
	v_cmp_eq_u32_e64 s[68:69], 0, v234
	v_cmp_eq_u32_e64 s[58:59], 0, v84
	s_nop 0
	v_and_b32_e32 v207, v156, v187
	s_nop 4
	v_cndmask_b32_e64 v222, v99, v158, s[66:67]
	v_cndmask_b32_e64 v221, v100, v158, s[64:65]
	v_cndmask_b32_e64 v220, v101, v158, s[62:63]
	v_cndmask_b32_e64 v223, v98, v158, s[68:69]
	v_cmp_eq_u32_e64 s[60:61], 0, v85
	v_cndmask_b32_e64 v213, v86, v158, s[16:17]
	v_cmp_eq_u32_e64 s[4:5], 0, v207
	v_cndmask_b32_e64 v219, v102, v158, s[60:61]
	v_cndmask_b32_e64 v207, v87, v158, s[4:5]
	v_and_b32_e32 v86, v156, v188
	v_and_b32_e32 v87, v157, v188
	v_cndmask_b32_e64 v218, v103, v158, s[58:59]
	v_and_b32_e32 v208, v156, v189
	v_cmp_eq_u32_e64 s[14:15], 0, v86
	v_and_b32_e32 v86, v157, v189
	v_cmp_eq_u32_e64 s[56:57], 0, v87
	v_cndmask_b32_e64 v211, v88, v158, s[14:15]
	v_cmp_eq_u32_e64 s[6:7], 0, v208
	v_cndmask_b32_e64 v217, v104, v158, s[56:57]
	v_cmp_eq_u32_e64 s[54:55], 0, v86
	v_cndmask_b32_e64 v208, v89, v158, s[6:7]
	v_and_b32_e32 v88, v156, v190
	v_and_b32_e32 v89, v157, v190
	v_cndmask_b32_e64 v215, v105, v158, s[54:55]
	v_cmp_eq_u32_e64 s[12:13], 0, v88
	v_cmp_eq_u32_e64 s[44:45], 0, v89
	v_cndmask_b32_e64 v90, v90, v158, s[12:13]
	v_cndmask_b32_e64 v216, v106, v158, s[44:45]
	v_cndmask_b32_e64 v105, v91, v158, s[50:51]
	v_cndmask_b32_e64 v106, v107, v158, s[52:53]
	v_cndmask_b32_e64 v103, v92, v158, s[46:47]
	v_cndmask_b32_e64 v104, v108, v158, s[48:49]
	v_cndmask_b32_e64 v101, v93, v158, s[40:41]
	v_cndmask_b32_e64 v102, v109, v158, s[42:43]
	v_cndmask_b32_e64 v99, v94, v158, s[36:37]
	v_cndmask_b32_e64 v100, v110, v158, s[38:39]
	v_cndmask_b32_e64 v95, v95, v158, s[30:31]
	v_cndmask_b32_e64 v98, v111, v158, s[34:35]
	v_cndmask_b32_e64 v93, v96, v158, s[26:27]
	v_cndmask_b32_e64 v94, v112, v158, s[28:29]
	v_cndmask_b32_e64 v91, v97, v158, s[22:23]
	v_cndmask_b32_e64 v92, v113, v158, s[24:25]
	v_max3_f32 v96, v212, v210, v214
	v_max3_f32 v247, v209, v222, v221
	v_max3_f32 v96, v96, v220, v223
	v_max3_f32 v247, v247, v213, v219
	v_max3_f32 v96, v96, v207, v218
	v_max3_f32 v247, v247, v211, v217
	v_max3_f32 v96, v96, v208, v215
	v_max3_f32 v247, v247, v90, v216
	v_max3_f32 v96, v96, v105, v106
	v_max3_f32 v247, v247, v103, v104
	v_max3_f32 v96, v96, v101, v102
	v_max3_f32 v247, v247, v99, v100
	v_max3_f32 v96, v96, v95, v98
	v_max3_f32 v247, v247, v93, v94
	v_max3_f32 v96, v96, v91, v92
	v_max_f32_e32 v96, v96, v247
	s_waitcnt vmcnt(0)
	ds_read_b64_tr_b16 v[138:139], v155 offset:49152
	ds_read_b64_tr_b16 v[140:141], v199 offset:51200
	ds_read_b64_tr_b16 v[134:135], v200 offset:49152
	ds_read_b64_tr_b16 v[136:137], v201 offset:51200
	v_mov_b32_e32 v246, v96
	v_mov_b32_e32 v247, v96
	ds_read_b64_tr_b16 v[86:87], v202 offset:49152
	ds_read_b64_tr_b16 v[88:89], v203 offset:51200
	ds_read_b64_tr_b16 v[82:83], v204 offset:49152
	ds_read_b64_tr_b16 v[84:85], v205 offset:51200
	v_permlane32_swap_b32_e32 v246, v247
	v_max3_f32 v96, v96, v246, v247
	v_add_f32_e32 v97, 0x41000000, v206
	v_cmp_gt_f32_e32 vcc, v96, v97
	s_cbranch_vccz .LBB0_2117
	s_nop 0
	v_cndmask_b32_e32 v97, v206, v96, vcc
	v_sub_f32_e32 v96, v206, v97
	v_exp_f32_e32 v96, v96
	v_mov_b32_e32 v206, v97
	v_mul_f32_e32 v192, v192, v96
	v_pk_mul_f32 v[80:81], v[80:81], v[96:97] op_sel_hi:[1,0]
	v_pk_mul_f32 v[78:79], v[78:79], v[96:97] op_sel_hi:[1,0]
	v_pk_mul_f32 v[76:77], v[76:77], v[96:97] op_sel_hi:[1,0]
	v_pk_mul_f32 v[74:75], v[74:75], v[96:97] op_sel_hi:[1,0]
	v_pk_mul_f32 v[72:73], v[72:73], v[96:97] op_sel_hi:[1,0]
	v_pk_mul_f32 v[70:71], v[70:71], v[96:97] op_sel_hi:[1,0]
	v_pk_mul_f32 v[68:69], v[68:69], v[96:97] op_sel_hi:[1,0]
	v_pk_mul_f32 v[66:67], v[66:67], v[96:97] op_sel_hi:[1,0]
	v_pk_mul_f32 v[64:65], v[64:65], v[96:97] op_sel_hi:[1,0]
	v_pk_mul_f32 v[62:63], v[62:63], v[96:97] op_sel_hi:[1,0]
	v_pk_mul_f32 v[60:61], v[60:61], v[96:97] op_sel_hi:[1,0]
	v_pk_mul_f32 v[58:59], v[58:59], v[96:97] op_sel_hi:[1,0]
	v_pk_mul_f32 v[56:57], v[56:57], v[96:97] op_sel_hi:[1,0]
	v_pk_mul_f32 v[54:55], v[54:55], v[96:97] op_sel_hi:[1,0]
	v_pk_mul_f32 v[52:53], v[52:53], v[96:97] op_sel_hi:[1,0]
	v_pk_mul_f32 v[50:51], v[50:51], v[96:97] op_sel_hi:[1,0]
	v_pk_mul_f32 v[48:49], v[48:49], v[96:97] op_sel_hi:[1,0]
	v_pk_mul_f32 v[46:47], v[46:47], v[96:97] op_sel_hi:[1,0]
	v_pk_mul_f32 v[44:45], v[44:45], v[96:97] op_sel_hi:[1,0]
	v_pk_mul_f32 v[42:43], v[42:43], v[96:97] op_sel_hi:[1,0]
	v_pk_mul_f32 v[40:41], v[40:41], v[96:97] op_sel_hi:[1,0]
	v_pk_mul_f32 v[38:39], v[38:39], v[96:97] op_sel_hi:[1,0]
	v_pk_mul_f32 v[36:37], v[36:37], v[96:97] op_sel_hi:[1,0]
	v_pk_mul_f32 v[34:35], v[34:35], v[96:97] op_sel_hi:[1,0]
	v_pk_mul_f32 v[32:33], v[32:33], v[96:97] op_sel_hi:[1,0]
	v_pk_mul_f32 v[30:31], v[30:31], v[96:97] op_sel_hi:[1,0]
	v_pk_mul_f32 v[28:29], v[28:29], v[96:97] op_sel_hi:[1,0]
	v_pk_mul_f32 v[26:27], v[26:27], v[96:97] op_sel_hi:[1,0]
	v_pk_mul_f32 v[24:25], v[24:25], v[96:97] op_sel_hi:[1,0]
	v_pk_mul_f32 v[22:23], v[22:23], v[96:97] op_sel_hi:[1,0]
	v_pk_mul_f32 v[20:21], v[20:21], v[96:97] op_sel_hi:[1,0]
	v_pk_mul_f32 v[18:19], v[18:19], v[96:97] op_sel_hi:[1,0]
; __device__ __forceinline__ unsigned cvtpk(float lo, float hi) { typedef __bf16 b2 __attribute__((ext_vector_type(2))); f32x2 v = {lo, hi}; b2 b = __builtin_convertvector(v, b2); return __builtin_bit_cast(unsigned, b); }
; __device__ __forceinline__ int crow(int r, int hi) { return (r & 3) + 8 * (r >> 2) + 4 * hi; }
; #define ATT_VREAD(dst, q_) do { const LAS char* vp_ = (const LAS char*)vb + (((q_) >> 1) * 32 + 16 * ((q_) & 1)) * VSTR; \
;         _Pragma("unroll") for (int d_ = 0; d_ < 4; ++d_) { dst[d_][0] = vtr(vp_ + voff[d_][0]); dst[d_][1] = vtr(vp_ + 8 * VSTR + voff[d_][1]); } } while (0)
;     ...
;         float rsa[4] = {0.f, 0.f, 0.f, 0.f};
; #pragma unroll
;         for (int r = 0; r < 16; ++r) { float p0 = __builtin_amdgcn_exp2f(s0[r] - mrun), p1 = __builtin_amdgcn_exp2f(s1[r] - mrun);
;             if (LAYER == 1) { const int kv = crow(r, hi); p0 = ((w0 >> kv) & 1u) ? p0 : 0.f; p1 = ((w1 >> kv) & 1u) ? p1 : 0.f; }
;             s0[r] = p0; s1[r] = p1; rsa[r & 3] += p0 + p1; }
;         lrun += (rsa[0] + rsa[1]) + (rsa[2] + rsa[3]);
; #pragma unroll
;         for (int s = 0; s < 2; ++s) {
;             v4u x; x.x = cvtpk(s0[8 * s + 0], s0[8 * s + 1]); x.y = cvtpk(s0[8 * s + 2], s0[8 * s + 3]); x.z = cvtpk(s0[8 * s + 4], s0[8 * s + 5]); x.w = cvtpk(s0[8 * s + 6], s0[8 * s + 7]); pb[0][s] = __builtin_bit_cast(bf16x8, x);
;             v4u y; y.x = cvtpk(s1[8 * s + 0], s1[8 * s + 1]); y.y = cvtpk(s1[8 * s + 2], s1[8 * s + 3]); y.z = cvtpk(s1[8 * s + 4], s1[8 * s + 5]); y.w = cvtpk(s1[8 * s + 6], s1[8 * s + 7]); pb[1][s] = __builtin_bit_cast(bf16x8, y); }
;     };
;     ...
;             if (wkb) { vb = sbb + KBUF + vlane; ATT_VREAD(vpre, 0); SM(wb0, wb1, b0, b1, pbb);
;                 ATT_VREAD(va, 1); __builtin_amdgcn_s_setprio(1); ATT_PV(vpre, pbb, 0); __builtin_amdgcn_s_setprio(0);
;                 ATT_VREAD(vbb, 2); __builtin_amdgcn_s_setprio(1); ATT_PV(va, pbb, 1); __builtin_amdgcn_s_setprio(0);
;                 ATT_VREAD(va, 3); __builtin_amdgcn_s_setprio(1); ATT_PV(vbb, pbb, 2); __builtin_amdgcn_s_setprio(0);
;                 __builtin_amdgcn_s_setprio(1); ATT_PV(va, pbb, 3); __builtin_amdgcn_s_setprio(0); }
.LBB0_2117:
	v_max_f32_e32 v246, 0xef800000, v206
	v_sub_f32_e32 v96, v212, v246
	v_sub_f32_e32 v97, v223, v246
	v_exp_f32_e32 v96, v96
	v_exp_f32_e32 v97, v97
	v_sub_f32_e32 v107, v210, v246
	v_sub_f32_e32 v113, v209, v246
	v_sub_f32_e32 v209, v213, v246
	v_sub_f32_e32 v210, v219, v246
	v_exp_f32_e32 v209, v209
	v_exp_f32_e32 v210, v210
	v_sub_f32_e32 v108, v222, v246
	v_add_f32_e32 v109, v96, v97
	v_exp_f32_e32 v107, v107
	v_exp_f32_e32 v108, v108
	v_add_f32_e32 v109, 0, v109
	v_sub_f32_e32 v110, v214, v246
	v_sub_f32_e32 v111, v221, v246
	v_sub_f32_e32 v207, v207, v246
	v_sub_f32_e32 v213, v218, v246
	v_add_f32_e32 v214, v209, v210
	v_exp_f32_e32 v110, v110
	v_exp_f32_e32 v111, v111
	v_sub_f32_e32 v156, v220, v246
	v_exp_f32_e32 v207, v207
	v_exp_f32_e32 v213, v213
	v_add_f32_e32 v109, v214, v109
	v_sub_f32_e32 v211, v211, v246
	v_sub_f32_e32 v214, v217, v246
	v_exp_f32_e32 v113, v113
	v_exp_f32_e32 v156, v156
	v_exp_f32_e32 v211, v211
	v_exp_f32_e32 v214, v214
	v_sub_f32_e32 v208, v208, v246
	v_sub_f32_e32 v215, v215, v246
	v_exp_f32_e32 v208, v208
	v_exp_f32_e32 v215, v215
	v_sub_f32_e32 v90, v90, v246
	v_add_f32_e32 v112, v107, v108
	v_exp_f32_e32 v90, v90
	v_add_f32_e32 v112, 0, v112
	v_add_f32_e32 v157, v110, v111
	v_add_f32_e32 v217, v207, v213
	v_add_f32_e32 v157, 0, v157
	v_add_f32_e32 v212, v113, v156
	v_add_f32_e32 v112, v217, v112
	v_add_f32_e32 v217, v211, v214
	v_sub_f32_e32 v216, v216, v246
	v_add_f32_e32 v212, 0, v212
	v_add_f32_e32 v157, v217, v157
	v_exp_f32_e32 v216, v216
	v_add_f32_e32 v217, v208, v215
	v_add_f32_e32 v212, v217, v212
	v_mov_b32_e32 v217, v90
	v_sub_f32_e32 v90, v105, v246
	v_exp_f32_e32 v90, v90
	v_sub_f32_e32 v105, v106, v246
	v_add_f32_e32 v106, v217, v216
	v_add_f32_e32 v106, v106, v109
	v_mov_b32_e32 v109, v90
	v_sub_f32_e32 v90, v103, v246
	v_exp_f32_e32 v218, v105
	v_exp_f32_e32 v105, v90
	v_sub_f32_e32 v103, v104, v246
	v_exp_f32_e32 v219, v103
	v_sub_f32_e32 v90, v101, v246
	v_exp_f32_e32 v103, v90
	v_sub_f32_e32 v101, v102, v246
	v_exp_f32_e32 v101, v101
	v_sub_f32_e32 v90, v99, v246
	v_exp_f32_e32 v90, v90
	v_sub_f32_e32 v99, v100, v246
	v_add_f32_e32 v102, v105, v219
	v_exp_f32_e32 v220, v99
	v_add_f32_e32 v102, v102, v157
	v_mov_b32_e32 v157, v101
	v_mov_b32_e32 v101, v90
	v_sub_f32_e32 v90, v95, v246
	v_exp_f32_e32 v90, v90
	v_sub_f32_e32 v95, v98, v246
	v_exp_f32_e32 v221, v95
	v_add_f32_e32 v98, v101, v220
	v_add_f32_e32 v98, v98, v106
	v_mov_b32_e32 v106, v90
	v_sub_f32_e32 v90, v93, v246
	v_exp_f32_e32 v90, v90
	v_add_f32_e32 v104, v109, v218
	v_sub_f32_e32 v93, v94, v246
	v_add_f32_e32 v104, v104, v112
	v_exp_f32_e32 v222, v93
	v_add_f32_e32 v94, v106, v221
	v_add_f32_e32 v94, v94, v104
	v_mov_b32_e32 v104, v90
	v_sub_f32_e32 v90, v91, v246
	v_sub_f32_e32 v91, v92, v246
	v_exp_f32_e32 v90, v90
	v_exp_f32_e32 v223, v91
	v_add_f32_e32 v92, v104, v222
	v_add_f32_e32 v100, v103, v157
	v_add_f32_e32 v92, v92, v102
	v_mov_b32_e32 v102, v90
	v_add_f32_e32 v100, v100, v212
	v_add_f32_e32 v90, v102, v223
	v_add_f32_e32 v90, v90, v100
	v_add_f32_e32 v91, v98, v94
	v_add_f32_e32 v90, v92, v90
	v_add_f32_e32 v224, v91, v90
	v_cvt_pk_bf16_f32 v90, v96, v107
	v_cvt_pk_bf16_f32 v91, v110, v113
	v_cvt_pk_bf16_f32 v92, v209, v207
	v_cvt_pk_bf16_f32 v93, v211, v208
	v_cvt_pk_bf16_f32 v94, v97, v108
	v_cvt_pk_bf16_f32 v95, v111, v156
	v_cvt_pk_bf16_f32 v96, v210, v213
	v_cvt_pk_bf16_f32 v98, v217, v109
	v_cvt_pk_bf16_f32 v99, v105, v103
	v_cvt_pk_bf16_f32 v100, v101, v106
	v_cvt_pk_bf16_f32 v101, v104, v102
	ds_read_b64_tr_b16 v[102:103], v155 offset:53248
	ds_read_b64_tr_b16 v[104:105], v199 offset:55296
	ds_read_b64_tr_b16 v[106:107], v200 offset:53248
	ds_read_b64_tr_b16 v[108:109], v201 offset:55296
	ds_read_b64_tr_b16 v[110:111], v202 offset:53248
	ds_read_b64_tr_b16 v[112:113], v203 offset:55296
	ds_read_b64_tr_b16 v[208:209], v204 offset:53248
	ds_read_b64_tr_b16 v[210:211], v205 offset:55296
	v_cvt_pk_bf16_f32 v97, v214, v215
	v_cvt_pk_bf16_f32 v212, v216, v218
	v_cvt_pk_bf16_f32 v213, v219, v157
	v_cvt_pk_bf16_f32 v214, v220, v221
	v_cvt_pk_bf16_f32 v215, v222, v223
	s_nop 0
	s_waitcnt lgkmcnt(12)
	v_mfma_f32_32x32x16_bf16 v[66:81], v[138:141], v[90:93], v[66:81]
	v_add_f32_e32 v192, v192, v224
	v_mfma_f32_32x32x16_bf16 v[50:65], v[134:137], v[90:93], v[50:65]
	s_waitcnt lgkmcnt(10)
	v_mfma_f32_32x32x16_bf16 v[34:49], v[86:89], v[90:93], v[34:49]
	s_waitcnt lgkmcnt(8)
	v_mfma_f32_32x32x16_bf16 v[18:33], v[82:85], v[90:93], v[18:33]
	s_nop 0
	ds_read_b64_tr_b16 v[82:83], v155 offset:57344
	ds_read_b64_tr_b16 v[84:85], v199 offset:59392
	ds_read_b64_tr_b16 v[86:87], v200 offset:57344
	ds_read_b64_tr_b16 v[88:89], v201 offset:59392
	ds_read_b64_tr_b16 v[90:91], v202 offset:57344
	ds_read_b64_tr_b16 v[92:93], v203 offset:59392
	ds_read_b64_tr_b16 v[134:135], v204 offset:57344
	ds_read_b64_tr_b16 v[136:137], v205 offset:59392
	s_nop 0
	s_waitcnt lgkmcnt(14)
	v_mfma_f32_32x32x16_bf16 v[66:81], v[102:105], v[98:101], v[66:81]
	s_waitcnt lgkmcnt(12)
	v_mfma_f32_32x32x16_bf16 v[50:65], v[106:109], v[98:101], v[50:65]
	s_waitcnt lgkmcnt(10)
	v_mfma_f32_32x32x16_bf16 v[34:49], v[110:113], v[98:101], v[34:49]
	s_waitcnt lgkmcnt(8)
	v_mfma_f32_32x32x16_bf16 v[18:33], v[208:211], v[98:101], v[18:33]
	s_nop 0
	ds_read_b64_tr_b16 v[98:99], v155 offset:61440
	ds_read_b64_tr_b16 v[100:101], v199 offset:63488
	ds_read_b64_tr_b16 v[102:103], v200 offset:61440
	ds_read_b64_tr_b16 v[104:105], v201 offset:63488
	ds_read_b64_tr_b16 v[106:107], v202 offset:61440
	ds_read_b64_tr_b16 v[108:109], v203 offset:63488
	ds_read_b64_tr_b16 v[110:111], v204 offset:61440
	ds_read_b64_tr_b16 v[112:113], v205 offset:63488
	s_nop 0
	s_waitcnt lgkmcnt(14)
	v_mfma_f32_32x32x16_bf16 v[66:81], v[82:85], v[94:97], v[66:81]
	s_waitcnt lgkmcnt(12)
	v_mfma_f32_32x32x16_bf16 v[50:65], v[86:89], v[94:97], v[50:65]
	s_waitcnt lgkmcnt(10)
	v_mfma_f32_32x32x16_bf16 v[34:49], v[90:93], v[94:97], v[34:49]
	s_waitcnt lgkmcnt(8)
	v_mfma_f32_32x32x16_bf16 v[18:33], v[134:137], v[94:97], v[18:33]
	s_nop 0
	s_nop 0
	s_waitcnt lgkmcnt(6)
	v_mfma_f32_32x32x16_bf16 v[66:81], v[98:101], v[212:215], v[66:81]
	s_waitcnt lgkmcnt(4)
	v_mfma_f32_32x32x16_bf16 v[50:65], v[102:105], v[212:215], v[50:65]
	s_waitcnt lgkmcnt(2)
	v_mfma_f32_32x32x16_bf16 v[34:49], v[106:109], v[212:215], v[34:49]
	s_waitcnt lgkmcnt(0)
	v_mfma_f32_32x32x16_bf16 v[18:33], v[110:113], v[212:215], v[18:33]
	s_nop 0

; #define ATT_ISSUE2(p_, st_) do { LAS unsigned char* sp_ = lds + (st_) * STG2; const int ta_ = dual ? (p_) : 2 * (p_), tb_ = dual ? (p_) : 2 * (p_) + 1; ATT_ISSUE1(u, ta_, sp_); ATT_ISSUEM(ta_, sp_ + 2 * STAGEB); \
;         if (dual || tb_ < u.ntiles) { ATT_ISSUE1(ub, tb_, sp_ + STAGEB); ATT_ISSUEM(tb_, sp_ + 2 * STAGEB + MSKB); } } while (0)
;     ...
;         for (int p = p0; p < npairs; ++p) {
;             asm volatile("s_waitcnt vmcnt(0)" ::: "memory");
;             __builtin_amdgcn_s_barrier(); asm volatile("" ::: "memory");
;             if (p + 1 < npairs) ATT_ISSUE2(p + 1, (p + 1) & 1);
.LBB0_3301:
	s_add_i32 s96, s97, 1
	s_waitcnt vmcnt(0)
	s_barrier
	v_readlane_b32 s98, v254, 11
	s_nop 3
	s_cmp_lt_u32 s98, 4
	s_cbranch_scc1 .Lstag_3301
	s_setprio 1

; #define LAS __attribute__((address_space(3)))
;     ...
;     auto QK = [&](const LAS unsigned char* sbase, f32x16& s0, f32x16& s1) {
;         const LAS unsigned char* kb = sbase + r32 * KSTR; const int kc0 = (koff >> 3) + hi;
; #pragma unroll
;         for (int r = 0; r < 16; ++r) { s0[r] = 0.f; s1[r] = 0.f; }
; #pragma unroll
;         for (int kh = 0; kh < NKS; kh += 4) {
;             bf16x8 ka[4][2];
; #pragma unroll
;             for (int ks = 0; ks < 4; ++ks) { const int ko = ((kc0 + 2 * (kh + ks)) ^ ksw) << 4; ka[ks][0] = *(const LAS bf16x8*)(kb + ko); ka[ks][1] = *(const LAS bf16x8*)(kb + 32 * KSTR + ko); }
;             __builtin_amdgcn_s_setprio(1);
; #pragma unroll
;             for (int ks = 0; ks < 4; ++ks) { s0 = __builtin_amdgcn_mfma_f32_32x32x16_bf16(ka[ks][0], qf[kh + ks], s0, 0, 0, 0); s1 = __builtin_amdgcn_mfma_f32_32x32x16_bf16(ka[ks][1], qf[kh + ks], s1, 0, 0, 0); }
;             __builtin_amdgcn_s_setprio(0);
;         }
;     };
;     ...
;             const bool wka = active && !(dual && hsel) && ta <= my_last && !(xmode & 1), wkb = active && !(dual && !hsel) && tb < u.ntiles && tb <= my_last && !(xmode & 1);
;             f32x16 a0, a1, b0, b1; bf16x8 pba[2][2], pbb[2][2]; s16x4 vpre[4][2], va[4][2], vbb[4][2];
;             unsigned wa0 = 0xffffffffu, wa1 = 0xffffffffu, wb0 = 0xffffffffu, wb1 = 0xffffffffu;
;             if (LAYER == 1) { const v2u ma = *(const LAS v2u*)(sa + 2 * STAGEB + (32 * sb + r32) * 8), mb = *(const LAS v2u*)(sa + 2 * STAGEB + MSKB + (32 * sb + r32) * 8); wa0 = ma.x; wa1 = ma.y; wb0 = mb.x; wb1 = mb.y; }
;             if (wka) QK(sa, a0, a1);
;             if (LAYER == 0) { if (wkb) QK(sbb, b0, b1); }
.LBB0_3316:
	s_bitcmp1_b32 s97, 0
	s_cselect_b32 s2, 0x10400, 0
	s_add_i32 s45, s2, 0
	s_add_i32 s4, s94, -1
	s_and_b64 s[2:3], s[24:25], exec
	s_cselect_b32 s2, s4, s97
	s_cmp_le_u32 s2, s91
	s_cselect_b64 s[2:3], -1, 0
	s_and_b64 s[2:3], s[28:29], s[2:3]
	v_cndmask_b32_e64 v146, 0, 1, s[2:3]
	v_cmp_ne_u32_e64 s[4:5], 1, v146
	v_add_u32_e32 v146, s45, v196
	s_andn2_b64 vcc, exec, s[2:3]
	v_add_u32_e32 v149, v146, v197
	v_add_u32_e32 v148, v146, v198
	v_add_u32_e32 v147, v146, v199
	v_add_u32_e32 v146, v146, v200
	s_cbranch_vccnz .LBB0_3318
	ds_read_b128 v[66:69], v149
	ds_read_b128 v[98:101], v149 offset:8192
	ds_read_b128 v[150:153], v148
	ds_read_b128 v[154:157], v148 offset:8192
	ds_read_b128 v[158:161], v147
	ds_read_b128 v[202:205], v147 offset:8192
	ds_read_b128 v[206:209], v146
	ds_read_b128 v[210:213], v146 offset:8192
	s_nop 0
	s_waitcnt lgkmcnt(0)
	v_mfma_f32_32x32x16_bf16 v[66:81], v[66:69], v[130:133], 0
	v_mfma_f32_32x32x16_bf16 v[98:113], v[98:101], v[130:133], 0
	v_mfma_f32_32x32x16_bf16 v[66:81], v[150:153], v[134:137], v[66:81]
	v_mfma_f32_32x32x16_bf16 v[98:113], v[154:157], v[134:137], v[98:113]
	v_mfma_f32_32x32x16_bf16 v[66:81], v[158:161], v[138:141], v[66:81]
	v_mfma_f32_32x32x16_bf16 v[98:113], v[202:205], v[138:141], v[98:113]
	v_mfma_f32_32x32x16_bf16 v[66:81], v[206:209], v[142:145], v[66:81]
	v_mfma_f32_32x32x16_bf16 v[98:113], v[210:213], v[142:145], v[98:113]
	s_nop 0
.LBB0_3318:
	s_and_b64 s[2:3], s[24:25], exec
	s_cselect_b32 s48, s94, s97
	s_cmp_lt_i32 s48, s89
	s_cselect_b64 s[2:3], -1, 0
	s_and_b64 s[2:3], s[30:31], s[2:3]
	s_cmp_le_u32 s48, s91
	s_cselect_b64 s[48:49], -1, 0
	s_and_b64 s[48:49], s[2:3], s[48:49]
	v_cndmask_b32_e64 v150, 0, 1, s[48:49]
	v_cmp_ne_u32_e64 s[2:3], 1, v150
	s_andn2_b64 vcc, exec, s[48:49]
	s_cbranch_vccnz .LBB0_3320
	ds_read_b128 v[82:85], v149 offset:32768
	ds_read_b128 v[114:117], v149 offset:40960
	ds_read_b128 v[150:153], v148 offset:32768
	ds_read_b128 v[154:157], v148 offset:40960
	ds_read_b128 v[158:161], v147 offset:32768
	ds_read_b128 v[202:205], v147 offset:40960
	ds_read_b128 v[206:209], v146 offset:32768
	ds_read_b128 v[146:149], v146 offset:40960
	s_nop 0
	s_waitcnt lgkmcnt(0)
	v_mfma_f32_32x32x16_bf16 v[82:97], v[82:85], v[130:133], 0
	v_mfma_f32_32x32x16_bf16 v[114:129], v[114:117], v[130:133], 0
	v_mfma_f32_32x32x16_bf16 v[82:97], v[150:153], v[134:137], v[82:97]
	v_mfma_f32_32x32x16_bf16 v[114:129], v[154:157], v[134:137], v[114:129]
	v_mfma_f32_32x32x16_bf16 v[82:97], v[158:161], v[138:141], v[82:97]
	v_mfma_f32_32x32x16_bf16 v[114:129], v[202:205], v[138:141], v[114:129]
	v_mfma_f32_32x32x16_bf16 v[82:97], v[206:209], v[142:145], v[82:97]
	v_mfma_f32_32x32x16_bf16 v[114:129], v[146:149], v[142:145], v[114:129]
	s_nop 0

; __device__ __forceinline__ unsigned cvtpk(float lo, float hi) { typedef __bf16 b2 __attribute__((ext_vector_type(2))); f32x2 v = {lo, hi}; b2 b = __builtin_convertvector(v, b2); return __builtin_bit_cast(unsigned, b); }
; __device__ __forceinline__ int crow(int r, int hi) { return (r & 3) + 8 * (r >> 2) + 4 * hi; }
; #define ATT_VREAD(dst, q_) do { const LAS char* vp_ = (const LAS char*)vb + (((q_) >> 1) * 32 + 16 * ((q_) & 1)) * VSTR; \
;         _Pragma("unroll") for (int d_ = 0; d_ < 4; ++d_) { dst[d_][0] = vtr(vp_ + voff[d_][0]); dst[d_][1] = vtr(vp_ + 8 * VSTR + voff[d_][1]); } } while (0)
;     ...
;         float rsa[4] = {0.f, 0.f, 0.f, 0.f};
; #pragma unroll
;         for (int r = 0; r < 16; ++r) { float p0 = __builtin_amdgcn_exp2f(s0[r] - mrun), p1 = __builtin_amdgcn_exp2f(s1[r] - mrun);
;             if (LAYER == 1) { const int kv = crow(r, hi); p0 = ((w0 >> kv) & 1u) ? p0 : 0.f; p1 = ((w1 >> kv) & 1u) ? p1 : 0.f; }
;             s0[r] = p0; s1[r] = p1; rsa[r & 3] += p0 + p1; }
;         lrun += (rsa[0] + rsa[1]) + (rsa[2] + rsa[3]);
; #pragma unroll
;         for (int s = 0; s < 2; ++s) {
;             v4u x; x.x = cvtpk(s0[8 * s + 0], s0[8 * s + 1]); x.y = cvtpk(s0[8 * s + 2], s0[8 * s + 3]); x.z = cvtpk(s0[8 * s + 4], s0[8 * s + 5]); x.w = cvtpk(s0[8 * s + 6], s0[8 * s + 7]); pb[0][s] = __builtin_bit_cast(bf16x8, x);
;             v4u y; y.x = cvtpk(s1[8 * s + 0], s1[8 * s + 1]); y.y = cvtpk(s1[8 * s + 2], s1[8 * s + 3]); y.z = cvtpk(s1[8 * s + 4], s1[8 * s + 5]); y.w = cvtpk(s1[8 * s + 6], s1[8 * s + 7]); pb[1][s] = __builtin_bit_cast(bf16x8, y); }
;     };
;     ...
;             if (wka) { vb = sa + KBUF + vlane; ATT_VREAD(vpre, 0); SM(wa0, wa1, a0, a1, pba);
;                 ATT_VREAD(va, 1); __builtin_amdgcn_s_setprio(1); ATT_PV(vpre, pba, 0); __builtin_amdgcn_s_setprio(0);
;                 ATT_VREAD(vbb, 2); __builtin_amdgcn_s_setprio(1); ATT_PV(va, pba, 1); __builtin_amdgcn_s_setprio(0);
;                 ATT_VREAD(va, 3); __builtin_amdgcn_s_setprio(1); ATT_PV(vbb, pba, 2); __builtin_amdgcn_s_setprio(0);
;                 __builtin_amdgcn_s_setprio(1); ATT_PV(va, pba, 3); __builtin_amdgcn_s_setprio(0); }
.LBB0_3323:
	v_sub_f32_e32 v66, v66, v170
	v_sub_f32_e32 v98, v98, v170
	v_sub_f32_e32 v68, v68, v170
	v_sub_f32_e32 v100, v100, v170
	v_exp_f32_e32 v66, v66
	v_exp_f32_e32 v98, v98
	v_sub_f32_e32 v67, v67, v170
	v_sub_f32_e32 v99, v99, v170
	v_exp_f32_e32 v68, v68
	v_exp_f32_e32 v100, v100
	v_sub_f32_e32 v69, v69, v170
	v_sub_f32_e32 v101, v101, v170
	v_exp_f32_e32 v67, v67
	v_exp_f32_e32 v99, v99
	v_exp_f32_e32 v69, v69
	v_exp_f32_e32 v101, v101
	v_sub_f32_e32 v70, v70, v170
	v_sub_f32_e32 v102, v102, v170
	v_sub_f32_e32 v72, v72, v170
	v_sub_f32_e32 v104, v104, v170
	v_exp_f32_e32 v70, v70
	v_exp_f32_e32 v102, v102
	v_exp_f32_e32 v72, v72
	v_exp_f32_e32 v104, v104
	v_sub_f32_e32 v71, v71, v170
	v_sub_f32_e32 v103, v103, v170
	v_sub_f32_e32 v73, v73, v170
	v_sub_f32_e32 v105, v105, v170
	v_exp_f32_e32 v71, v71
	v_exp_f32_e32 v103, v103
	v_exp_f32_e32 v73, v73
	v_exp_f32_e32 v105, v105
	v_sub_f32_e32 v74, v74, v170
	v_sub_f32_e32 v106, v106, v170
	v_sub_f32_e32 v76, v76, v170
	v_sub_f32_e32 v108, v108, v170
	v_exp_f32_e32 v74, v74
	v_exp_f32_e32 v106, v106
	v_exp_f32_e32 v76, v76
	v_exp_f32_e32 v108, v108
	v_sub_f32_e32 v75, v75, v170
	v_sub_f32_e32 v107, v107, v170
	v_sub_f32_e32 v77, v77, v170
	v_sub_f32_e32 v109, v109, v170
	v_exp_f32_e32 v75, v75
	v_exp_f32_e32 v107, v107
	v_exp_f32_e32 v77, v77
	v_exp_f32_e32 v109, v109
	v_sub_f32_e32 v78, v78, v170
	v_sub_f32_e32 v110, v110, v170
	v_sub_f32_e32 v80, v80, v170
	v_sub_f32_e32 v112, v112, v170
	ds_read_b64_tr_b16 v[222:223], v201 offset:20480
	ds_read_b64_tr_b16 v[224:225], v202 offset:22528
	ds_read_b64_tr_b16 v[226:227], v203 offset:20480
	ds_read_b64_tr_b16 v[228:229], v204 offset:22528
	ds_read_b64_tr_b16 v[230:231], v205 offset:20480
	ds_read_b64_tr_b16 v[232:233], v206 offset:22528
	ds_read_b64_tr_b16 v[234:235], v207 offset:20480
	ds_read_b64_tr_b16 v[236:237], v208 offset:22528
	v_exp_f32_e32 v78, v78
	v_exp_f32_e32 v110, v110
	v_exp_f32_e32 v80, v80
	v_exp_f32_e32 v112, v112
	v_sub_f32_e32 v79, v79, v170
	v_sub_f32_e32 v111, v111, v170
	v_sub_f32_e32 v81, v81, v170
	v_sub_f32_e32 v113, v113, v170
	v_exp_f32_e32 v79, v79
	v_exp_f32_e32 v111, v111
	v_exp_f32_e32 v81, v81
	v_exp_f32_e32 v113, v113
	s_nop 0
	v_pk_add_f32 v[210:211], v[66:67], v[68:69]
	v_pk_add_f32 v[212:213], v[70:71], v[72:73]
	v_pk_add_f32 v[214:215], v[74:75], v[76:77]
	v_pk_add_f32 v[216:217], v[78:79], v[80:81]
	v_pk_add_f32 v[210:211], v[210:211], v[98:99]
	v_pk_add_f32 v[212:213], v[212:213], v[100:101]
	v_pk_add_f32 v[214:215], v[214:215], v[102:103]
	v_pk_add_f32 v[216:217], v[216:217], v[104:105]
	v_pk_add_f32 v[210:211], v[210:211], v[106:107]
	v_pk_add_f32 v[212:213], v[212:213], v[108:109]
	v_pk_add_f32 v[214:215], v[214:215], v[110:111]
	v_pk_add_f32 v[216:217], v[216:217], v[112:113]
	v_pk_add_f32 v[210:211], v[210:211], v[212:213]
	v_pk_add_f32 v[214:215], v[214:215], v[216:217]
	v_pk_add_f32 v[210:211], v[210:211], v[214:215]
	v_add_f32_e32 v209, v210, v211
	v_cvt_pk_bf16_f32 v216, v102, v103
	v_cvt_pk_bf16_f32 v214, v98, v99
	v_cvt_pk_bf16_f32 v212, v70, v71
	v_cvt_pk_bf16_f32 v210, v66, v67
	v_cvt_pk_bf16_f32 v211, v68, v69
	v_cvt_pk_bf16_f32 v213, v72, v73
	v_cvt_pk_bf16_f32 v215, v100, v101
	v_cvt_pk_bf16_f32 v217, v104, v105
	v_cvt_pk_bf16_f32 v218, v74, v75
	v_cvt_pk_bf16_f32 v219, v76, v77
	v_cvt_pk_bf16_f32 v220, v78, v79
	v_cvt_pk_bf16_f32 v221, v80, v81
	v_cvt_pk_bf16_f32 v238, v106, v107
	v_cvt_pk_bf16_f32 v239, v108, v109
	v_cvt_pk_bf16_f32 v240, v110, v111
	v_cvt_pk_bf16_f32 v241, v112, v113
	s_nop 0
	s_waitcnt lgkmcnt(8)
	v_mfma_f32_32x32x16_bf16 v[50:65], v[150:153], v[210:213], v[50:65]
	v_add_f32_e32 v167, v167, v209
	v_mfma_f32_32x32x16_bf16 v[34:49], v[146:149], v[210:213], v[34:49]
	v_mfma_f32_32x32x16_bf16 v[18:33], v[158:161], v[210:213], v[18:33]
	v_mfma_f32_32x32x16_bf16 v[2:17], v[154:157], v[210:213], v[2:17]
	s_nop 0
	ds_read_b64_tr_b16 v[146:147], v201 offset:24576
	ds_read_b64_tr_b16 v[148:149], v202 offset:26624
	ds_read_b64_tr_b16 v[150:151], v203 offset:24576
	ds_read_b64_tr_b16 v[152:153], v204 offset:26624
	ds_read_b64_tr_b16 v[154:155], v205 offset:24576
	ds_read_b64_tr_b16 v[156:157], v206 offset:26624
	ds_read_b64_tr_b16 v[158:159], v207 offset:24576
	ds_read_b64_tr_b16 v[160:161], v208 offset:26624
	s_nop 0
	s_waitcnt lgkmcnt(14)
	v_mfma_f32_32x32x16_bf16 v[50:65], v[222:225], v[218:221], v[50:65]
	s_waitcnt lgkmcnt(12)
	v_mfma_f32_32x32x16_bf16 v[34:49], v[226:229], v[218:221], v[34:49]
	s_waitcnt lgkmcnt(10)
	v_mfma_f32_32x32x16_bf16 v[18:33], v[230:233], v[218:221], v[18:33]
	s_waitcnt lgkmcnt(8)
	v_mfma_f32_32x32x16_bf16 v[2:17], v[234:237], v[218:221], v[2:17]
	s_nop 0
	ds_read_b64_tr_b16 v[210:211], v201 offset:28672
	ds_read_b64_tr_b16 v[212:213], v202 offset:30720
	ds_read_b64_tr_b16 v[218:219], v203 offset:28672
	ds_read_b64_tr_b16 v[220:221], v204 offset:30720
	ds_read_b64_tr_b16 v[222:223], v205 offset:28672
	ds_read_b64_tr_b16 v[224:225], v206 offset:30720
	ds_read_b64_tr_b16 v[226:227], v207 offset:28672
	ds_read_b64_tr_b16 v[228:229], v208 offset:30720
	s_nop 0
	s_waitcnt lgkmcnt(14)
	v_mfma_f32_32x32x16_bf16 v[50:65], v[146:149], v[214:217], v[50:65]
	s_waitcnt lgkmcnt(12)
	v_mfma_f32_32x32x16_bf16 v[34:49], v[150:153], v[214:217], v[34:49]
	s_waitcnt lgkmcnt(10)
	v_mfma_f32_32x32x16_bf16 v[18:33], v[154:157], v[214:217], v[18:33]
	s_waitcnt lgkmcnt(8)
	v_mfma_f32_32x32x16_bf16 v[2:17], v[158:161], v[214:217], v[2:17]
	s_nop 0
	s_nop 0
	s_waitcnt lgkmcnt(6)
	v_mfma_f32_32x32x16_bf16 v[50:65], v[210:213], v[238:241], v[50:65]
	s_waitcnt lgkmcnt(4)
	v_mfma_f32_32x32x16_bf16 v[34:49], v[218:221], v[238:241], v[34:49]
	s_waitcnt lgkmcnt(2)
	v_mfma_f32_32x32x16_bf16 v[18:33], v[222:225], v[238:241], v[18:33]
	s_waitcnt lgkmcnt(0)
	v_mfma_f32_32x32x16_bf16 v[2:17], v[226:229], v[238:241], v[2:17]
	s_nop 0

; __device__ __forceinline__ unsigned cvtpk(float lo, float hi) { typedef __bf16 b2 __attribute__((ext_vector_type(2))); f32x2 v = {lo, hi}; b2 b = __builtin_convertvector(v, b2); return __builtin_bit_cast(unsigned, b); }
; __device__ __forceinline__ int crow(int r, int hi) { return (r & 3) + 8 * (r >> 2) + 4 * hi; }
; #define ATT_VREAD(dst, q_) do { const LAS char* vp_ = (const LAS char*)vb + (((q_) >> 1) * 32 + 16 * ((q_) & 1)) * VSTR; \
;         _Pragma("unroll") for (int d_ = 0; d_ < 4; ++d_) { dst[d_][0] = vtr(vp_ + voff[d_][0]); dst[d_][1] = vtr(vp_ + 8 * VSTR + voff[d_][1]); } } while (0)
;     ...
;         float rsa[4] = {0.f, 0.f, 0.f, 0.f};
; #pragma unroll
;         for (int r = 0; r < 16; ++r) { float p0 = __builtin_amdgcn_exp2f(s0[r] - mrun), p1 = __builtin_amdgcn_exp2f(s1[r] - mrun);
;             if (LAYER == 1) { const int kv = crow(r, hi); p0 = ((w0 >> kv) & 1u) ? p0 : 0.f; p1 = ((w1 >> kv) & 1u) ? p1 : 0.f; }
;             s0[r] = p0; s1[r] = p1; rsa[r & 3] += p0 + p1; }
;         lrun += (rsa[0] + rsa[1]) + (rsa[2] + rsa[3]);
; #pragma unroll
;         for (int s = 0; s < 2; ++s) {
;             v4u x; x.x = cvtpk(s0[8 * s + 0], s0[8 * s + 1]); x.y = cvtpk(s0[8 * s + 2], s0[8 * s + 3]); x.z = cvtpk(s0[8 * s + 4], s0[8 * s + 5]); x.w = cvtpk(s0[8 * s + 6], s0[8 * s + 7]); pb[0][s] = __builtin_bit_cast(bf16x8, x);
;             v4u y; y.x = cvtpk(s1[8 * s + 0], s1[8 * s + 1]); y.y = cvtpk(s1[8 * s + 2], s1[8 * s + 3]); y.z = cvtpk(s1[8 * s + 4], s1[8 * s + 5]); y.w = cvtpk(s1[8 * s + 6], s1[8 * s + 7]); pb[1][s] = __builtin_bit_cast(bf16x8, y); }
;     };
;     ...
;             if (wkb) { vb = sbb + KBUF + vlane; ATT_VREAD(vpre, 0); SM(wb0, wb1, b0, b1, pbb);
;                 ATT_VREAD(va, 1); __builtin_amdgcn_s_setprio(1); ATT_PV(vpre, pbb, 0); __builtin_amdgcn_s_setprio(0);
;                 ATT_VREAD(vbb, 2); __builtin_amdgcn_s_setprio(1); ATT_PV(va, pbb, 1); __builtin_amdgcn_s_setprio(0);
;                 ATT_VREAD(va, 3); __builtin_amdgcn_s_setprio(1); ATT_PV(vbb, pbb, 2); __builtin_amdgcn_s_setprio(0);
;                 __builtin_amdgcn_s_setprio(1); ATT_PV(va, pbb, 3); __builtin_amdgcn_s_setprio(0); }
.LBB0_3327:
	v_sub_f32_e32 v82, v82, v170
	v_sub_f32_e32 v114, v114, v170
	v_sub_f32_e32 v84, v84, v170
	v_sub_f32_e32 v116, v116, v170
	v_exp_f32_e32 v82, v82
	v_exp_f32_e32 v114, v114
	v_sub_f32_e32 v83, v83, v170
	v_sub_f32_e32 v115, v115, v170
	v_exp_f32_e32 v84, v84
	v_exp_f32_e32 v116, v116
	v_sub_f32_e32 v85, v85, v170
	v_sub_f32_e32 v117, v117, v170
	v_exp_f32_e32 v83, v83
	v_exp_f32_e32 v115, v115
	v_exp_f32_e32 v85, v85
	v_exp_f32_e32 v117, v117
	v_sub_f32_e32 v86, v86, v170
	v_sub_f32_e32 v118, v118, v170
	v_sub_f32_e32 v88, v88, v170
	v_sub_f32_e32 v120, v120, v170
	v_exp_f32_e32 v86, v86
	v_exp_f32_e32 v118, v118
	v_exp_f32_e32 v88, v88
	v_exp_f32_e32 v120, v120
	v_sub_f32_e32 v87, v87, v170
	v_sub_f32_e32 v119, v119, v170
	v_sub_f32_e32 v89, v89, v170
	v_sub_f32_e32 v121, v121, v170
	v_exp_f32_e32 v87, v87
	v_exp_f32_e32 v119, v119
	v_exp_f32_e32 v89, v89
	v_exp_f32_e32 v121, v121
	v_sub_f32_e32 v90, v90, v170
	v_sub_f32_e32 v122, v122, v170
	v_sub_f32_e32 v92, v92, v170
	v_sub_f32_e32 v124, v124, v170
	v_exp_f32_e32 v90, v90
	v_exp_f32_e32 v122, v122
	v_exp_f32_e32 v92, v92
	v_exp_f32_e32 v124, v124
	v_sub_f32_e32 v91, v91, v170
	v_sub_f32_e32 v123, v123, v170
	v_sub_f32_e32 v93, v93, v170
	v_sub_f32_e32 v125, v125, v170
	v_exp_f32_e32 v91, v91
	v_exp_f32_e32 v123, v123
	v_exp_f32_e32 v93, v93
	v_exp_f32_e32 v125, v125
	v_sub_f32_e32 v94, v94, v170
	v_sub_f32_e32 v126, v126, v170
	v_sub_f32_e32 v96, v96, v170
	v_sub_f32_e32 v128, v128, v170
	ds_read_b64_tr_b16 v[222:223], v201 offset:53248
	ds_read_b64_tr_b16 v[224:225], v202 offset:55296
	ds_read_b64_tr_b16 v[226:227], v203 offset:53248
	ds_read_b64_tr_b16 v[228:229], v204 offset:55296
	ds_read_b64_tr_b16 v[230:231], v205 offset:53248
	ds_read_b64_tr_b16 v[232:233], v206 offset:55296
	ds_read_b64_tr_b16 v[234:235], v207 offset:53248
	ds_read_b64_tr_b16 v[236:237], v208 offset:55296
	v_exp_f32_e32 v94, v94
	v_exp_f32_e32 v126, v126
	v_exp_f32_e32 v96, v96
	v_exp_f32_e32 v128, v128
	v_sub_f32_e32 v95, v95, v170
	v_sub_f32_e32 v127, v127, v170
	v_sub_f32_e32 v97, v97, v170
	v_sub_f32_e32 v129, v129, v170
	v_exp_f32_e32 v95, v95
	v_exp_f32_e32 v127, v127
	v_exp_f32_e32 v97, v97
	v_exp_f32_e32 v129, v129
	s_nop 0
	v_pk_add_f32 v[210:211], v[82:83], v[84:85]
	v_pk_add_f32 v[212:213], v[86:87], v[88:89]
	v_pk_add_f32 v[214:215], v[90:91], v[92:93]
	v_pk_add_f32 v[216:217], v[94:95], v[96:97]
	v_pk_add_f32 v[210:211], v[210:211], v[114:115]
	v_pk_add_f32 v[212:213], v[212:213], v[116:117]
	v_pk_add_f32 v[214:215], v[214:215], v[118:119]
	v_pk_add_f32 v[216:217], v[216:217], v[120:121]
	v_pk_add_f32 v[210:211], v[210:211], v[122:123]
	v_pk_add_f32 v[212:213], v[212:213], v[124:125]
	v_pk_add_f32 v[214:215], v[214:215], v[126:127]
	v_pk_add_f32 v[216:217], v[216:217], v[128:129]
	v_pk_add_f32 v[210:211], v[210:211], v[212:213]
	v_pk_add_f32 v[214:215], v[214:215], v[216:217]
	v_pk_add_f32 v[210:211], v[210:211], v[214:215]
	v_add_f32_e32 v209, v210, v211
	v_cvt_pk_bf16_f32 v216, v118, v119
	v_cvt_pk_bf16_f32 v214, v114, v115
	v_cvt_pk_bf16_f32 v212, v86, v87
	v_cvt_pk_bf16_f32 v210, v82, v83
	v_cvt_pk_bf16_f32 v211, v84, v85
	v_cvt_pk_bf16_f32 v213, v88, v89
	v_cvt_pk_bf16_f32 v215, v116, v117
	v_cvt_pk_bf16_f32 v217, v120, v121
	v_cvt_pk_bf16_f32 v218, v90, v91
	v_cvt_pk_bf16_f32 v219, v92, v93
	v_cvt_pk_bf16_f32 v220, v94, v95
	v_cvt_pk_bf16_f32 v221, v96, v97
	v_cvt_pk_bf16_f32 v238, v122, v123
	v_cvt_pk_bf16_f32 v239, v124, v125
	v_cvt_pk_bf16_f32 v240, v126, v127
	v_cvt_pk_bf16_f32 v241, v128, v129
	s_nop 0
	s_waitcnt lgkmcnt(8)
	v_mfma_f32_32x32x16_bf16 v[50:65], v[150:153], v[210:213], v[50:65]
	v_add_f32_e32 v167, v167, v209
	v_mfma_f32_32x32x16_bf16 v[34:49], v[146:149], v[210:213], v[34:49]
	v_mfma_f32_32x32x16_bf16 v[18:33], v[158:161], v[210:213], v[18:33]
	v_mfma_f32_32x32x16_bf16 v[2:17], v[154:157], v[210:213], v[2:17]
	s_nop 0
	ds_read_b64_tr_b16 v[146:147], v201 offset:57344
	ds_read_b64_tr_b16 v[148:149], v202 offset:59392
	ds_read_b64_tr_b16 v[150:151], v203 offset:57344
	ds_read_b64_tr_b16 v[152:153], v204 offset:59392
	ds_read_b64_tr_b16 v[154:155], v205 offset:57344
	ds_read_b64_tr_b16 v[156:157], v206 offset:59392
	ds_read_b64_tr_b16 v[158:159], v207 offset:57344
	ds_read_b64_tr_b16 v[160:161], v208 offset:59392
	s_nop 0
	s_waitcnt lgkmcnt(14)
	v_mfma_f32_32x32x16_bf16 v[50:65], v[222:225], v[218:221], v[50:65]
	s_waitcnt lgkmcnt(12)
	v_mfma_f32_32x32x16_bf16 v[34:49], v[226:229], v[218:221], v[34:49]
	s_waitcnt lgkmcnt(10)
	v_mfma_f32_32x32x16_bf16 v[18:33], v[230:233], v[218:221], v[18:33]
	s_waitcnt lgkmcnt(8)
	v_mfma_f32_32x32x16_bf16 v[2:17], v[234:237], v[218:221], v[2:17]
	s_nop 0
	ds_read_b64_tr_b16 v[210:211], v201 offset:61440
	ds_read_b64_tr_b16 v[212:213], v202 offset:63488
	ds_read_b64_tr_b16 v[218:219], v203 offset:61440
	ds_read_b64_tr_b16 v[220:221], v204 offset:63488
	ds_read_b64_tr_b16 v[202:203], v205 offset:61440
	ds_read_b64_tr_b16 v[204:205], v206 offset:63488
	ds_read_b64_tr_b16 v[206:207], v207 offset:61440
	ds_read_b64_tr_b16 v[208:209], v208 offset:63488
	s_nop 0
	s_waitcnt lgkmcnt(14)
	v_mfma_f32_32x32x16_bf16 v[50:65], v[146:149], v[214:217], v[50:65]
	s_waitcnt lgkmcnt(12)
	v_mfma_f32_32x32x16_bf16 v[34:49], v[150:153], v[214:217], v[34:49]
	s_waitcnt lgkmcnt(10)
	v_mfma_f32_32x32x16_bf16 v[18:33], v[154:157], v[214:217], v[18:33]
	s_waitcnt lgkmcnt(8)
	v_mfma_f32_32x32x16_bf16 v[2:17], v[158:161], v[214:217], v[2:17]
	s_nop 0
	s_nop 0
	s_waitcnt lgkmcnt(6)
	v_mfma_f32_32x32x16_bf16 v[50:65], v[210:213], v[238:241], v[50:65]
	s_waitcnt lgkmcnt(4)
	v_mfma_f32_32x32x16_bf16 v[34:49], v[218:221], v[238:241], v[34:49]
	s_waitcnt lgkmcnt(2)
	v_mfma_f32_32x32x16_bf16 v[18:33], v[202:205], v[238:241], v[18:33]
	s_waitcnt lgkmcnt(0)
	v_mfma_f32_32x32x16_bf16 v[2:17], v[206:209], v[238:241], v[2:17]
	s_nop 0

; #define LAS __attribute__((address_space(3)))
;     ...
;     const float ltot = lrun + __shfl_xor(lrun, 32);
;     const float inv = active ? __builtin_amdgcn_rcpf(ltot) : 0.f;
;     if (u.split >= 0) {
;         if (active) { const int hd = LAYER == 0 ? myhead * 2 + map : u.head * 4 + r4;
;             float* pr = (float*)(F.ws + WS_APART) + (((size_t)u.split * NS + (qrow - NP)) * 32 + hd) * 130;
; #pragma unroll
;             for (int d = 0; d < 4; ++d)
; #pragma unroll
;                 for (int rg = 0; rg < 4; ++rg) { float* p = pr + d * 32 + 8 * rg + 4 * hi; p[0] = o[d][4 * rg]; p[1] = o[d][4 * rg + 1]; p[2] = o[d][4 * rg + 2]; p[3] = o[d][4 * rg + 3]; }
;             if (hi == 0) { pr[128] = mrun; pr[129] = ltot; } }
;         return;
;     }
;     bf16* OB = (bf16*)(F.ws + WS_OB);
;     if (LAYER == 0) {
;         LAS float* xch = (LAS float*)lds;
;         if (map == 1 && active) { const float sc = inv * lam;
; #pragma unroll
;             for (int d = 0; d < 4; ++d)
; #pragma unroll
;                 for (int r = 0; r < 16; ++r) xch[(sb * 64 + d * 16 + r) * 64 + lane] = o[d][r] * sc; }
.LBB0_3331:
	s_setprio 0
	v_and_b32_e32 v67, 64, v184
	v_xor_b32_e32 v66, 32, v184
	v_add_u32_e32 v67, 64, v67
	v_cmp_lt_i32_e32 vcc, v66, v67
	s_waitcnt lgkmcnt(0)
	s_barrier
	s_lshl_b32 s4, s23, 7
	v_cndmask_b32_e32 v66, v184, v66, vcc
	v_lshlrev_b32_e32 v158, 2, v66
	ds_bpermute_b32 v66, v158, v167
	s_cmp_lt_i32 s22, 0
	s_mov_b64 s[2:3], -1
	s_waitcnt lgkmcnt(0)
	v_add_f32_e32 v171, v167, v66
	s_cbranch_scc0 .LBB0_3337
	v_rcp_f32_e32 v76, v171
	s_andn2_b64 vcc, exec, s[8:9]
	s_cbranch_vccnz .LBB0_3334
	v_mul_f32_e32 v66, v1, v76
	v_mul_f32_e32 v67, v50, v66
	v_lshl_add_u32 v68, v186, 2, s72
	v_mul_f32_e32 v69, v51, v66
	ds_write2st64_b32 v68, v67, v69 offset1:1
	v_mul_f32_e32 v67, v52, v66
	v_mul_f32_e32 v69, v53, v66
	ds_write2st64_b32 v68, v67, v69 offset0:2 offset1:3
	v_mul_f32_e32 v67, v54, v66
	v_mul_f32_e32 v69, v55, v66
	ds_write2st64_b32 v68, v67, v69 offset0:4 offset1:5
	v_mul_f32_e32 v67, v56, v66
	v_mul_f32_e32 v69, v57, v66
	ds_write2st64_b32 v68, v67, v69 offset0:6 offset1:7
	v_mul_f32_e32 v67, v58, v66
	v_mul_f32_e32 v69, v59, v66
	ds_write2st64_b32 v68, v67, v69 offset0:8 offset1:9
	v_mul_f32_e32 v67, v60, v66
	v_mul_f32_e32 v69, v61, v66
	ds_write2st64_b32 v68, v67, v69 offset0:10 offset1:11
	v_mul_f32_e32 v67, v62, v66
	v_mul_f32_e32 v69, v63, v66
	ds_write2st64_b32 v68, v67, v69 offset0:12 offset1:13
	v_mul_f32_e32 v67, v64, v66
	v_mul_f32_e32 v69, v65, v66
	ds_write2st64_b32 v68, v67, v69 offset0:14 offset1:15
	v_mul_f32_e32 v67, v34, v66
	v_mul_f32_e32 v69, v35, v66
	ds_write2st64_b32 v68, v67, v69 offset0:16 offset1:17
	v_mul_f32_e32 v67, v36, v66
	v_mul_f32_e32 v69, v37, v66
	ds_write2st64_b32 v68, v67, v69 offset0:18 offset1:19
	v_mul_f32_e32 v67, v38, v66
	v_mul_f32_e32 v69, v39, v66
	ds_write2st64_b32 v68, v67, v69 offset0:20 offset1:21
	v_mul_f32_e32 v67, v40, v66
	v_mul_f32_e32 v69, v41, v66
	ds_write2st64_b32 v68, v67, v69 offset0:22 offset1:23
	v_mul_f32_e32 v67, v42, v66
	v_mul_f32_e32 v69, v43, v66
	ds_write2st64_b32 v68, v67, v69 offset0:24 offset1:25
	v_mul_f32_e32 v67, v44, v66
	v_mul_f32_e32 v69, v45, v66
	ds_write2st64_b32 v68, v67, v69 offset0:26 offset1:27
	v_mul_f32_e32 v67, v46, v66
	v_mul_f32_e32 v69, v47, v66
	ds_write2st64_b32 v68, v67, v69 offset0:28 offset1:29
	v_mul_f32_e32 v67, v48, v66
	v_mul_f32_e32 v69, v49, v66
	ds_write2st64_b32 v68, v67, v69 offset0:30 offset1:31
	v_mul_f32_e32 v67, v18, v66
	v_mul_f32_e32 v69, v19, v66
	ds_write2st64_b32 v68, v67, v69 offset0:32 offset1:33
	v_mul_f32_e32 v67, v20, v66
	v_mul_f32_e32 v69, v21, v66
	ds_write2st64_b32 v68, v67, v69 offset0:34 offset1:35
	v_mul_f32_e32 v67, v22, v66
	v_mul_f32_e32 v69, v23, v66
	ds_write2st64_b32 v68, v67, v69 offset0:36 offset1:37
	v_mul_f32_e32 v67, v24, v66
	v_mul_f32_e32 v69, v25, v66
	ds_write2st64_b32 v68, v67, v69 offset0:38 offset1:39
	v_mul_f32_e32 v67, v26, v66
	v_mul_f32_e32 v69, v27, v66
	ds_write2st64_b32 v68, v67, v69 offset0:40 offset1:41
	v_mul_f32_e32 v67, v28, v66
	v_mul_f32_e32 v69, v29, v66
	ds_write2st64_b32 v68, v67, v69 offset0:42 offset1:43
	v_mul_f32_e32 v67, v30, v66
	v_mul_f32_e32 v69, v31, v66
	ds_write2st64_b32 v68, v67, v69 offset0:44 offset1:45
	v_mul_f32_e32 v67, v32, v66
	v_mul_f32_e32 v69, v33, v66
	ds_write2st64_b32 v68, v67, v69 offset0:46 offset1:47
	v_mul_f32_e32 v67, v2, v66
	v_mul_f32_e32 v69, v3, v66
	ds_write2st64_b32 v68, v67, v69 offset0:48 offset1:49
	v_mul_f32_e32 v67, v4, v66
	v_mul_f32_e32 v69, v5, v66
	ds_write2st64_b32 v68, v67, v69 offset0:50 offset1:51
	v_mul_f32_e32 v67, v6, v66
	v_mul_f32_e32 v69, v7, v66
	ds_write2st64_b32 v68, v67, v69 offset0:52 offset1:53
	v_mul_f32_e32 v67, v8, v66
	v_mul_f32_e32 v69, v9, v66
	ds_write2st64_b32 v68, v67, v69 offset0:54 offset1:55
	v_mul_f32_e32 v67, v10, v66
	v_mul_f32_e32 v69, v11, v66
	ds_write2st64_b32 v68, v67, v69 offset0:56 offset1:57
	v_mul_f32_e32 v67, v12, v66
	v_mul_f32_e32 v69, v13, v66
	ds_write2st64_b32 v68, v67, v69 offset0:58 offset1:59
	v_mul_f32_e32 v67, v14, v66
	v_mul_f32_e32 v69, v15, v66
	ds_write2st64_b32 v68, v67, v69 offset0:60 offset1:61
	v_mul_f32_e32 v67, v16, v66
	v_mul_f32_e32 v66, v17, v66
	ds_write2st64_b32 v68, v67, v66 offset0:62 offset1:63
